# GEMM K-loops: last four LDS-DMA pieces of each 6-piece load segment issued inside the following MFMA burst (vmcnt 8 -> 4)
# speedup vs baseline: 1.0021x; 1.0021x over previous
.Lskw_P1:
	s_waitcnt lgkmcnt(0)
	s_barrier
	s_setprio 1
	s_waitcnt lgkmcnt(0)
	v_mfma_f32_16x16x32_bf16 v[124:127], v[148:151], v[186:189], v[124:127]
	v_mfma_f32_16x16x32_bf16 v[120:123], v[156:159], v[186:189], v[120:123]
	v_mfma_f32_16x16x32_bf16 v[108:111], v[148:151], v[194:197], v[108:111]
	v_mfma_f32_16x16x32_bf16 v[104:107], v[156:159], v[194:197], v[104:107]
	v_mfma_f32_16x16x32_bf16 v[92:95], v[148:151], v[202:205], v[92:95]
	v_mfma_f32_16x16x32_bf16 v[88:91], v[156:159], v[202:205], v[88:91]
	v_mfma_f32_16x16x32_bf16 v[76:79], v[148:151], v[210:213], v[76:79]
	v_mfma_f32_16x16x32_bf16 v[72:75], v[156:159], v[210:213], v[72:75]
	v_mfma_f32_16x16x32_bf16 v[124:127], v[152:155], v[190:193], v[124:127]
	v_mfma_f32_16x16x32_bf16 v[120:123], v[160:163], v[190:193], v[120:123]
	v_mfma_f32_16x16x32_bf16 v[108:111], v[152:155], v[198:201], v[108:111]
	v_mfma_f32_16x16x32_bf16 v[104:107], v[160:163], v[198:201], v[104:107]
	v_mfma_f32_16x16x32_bf16 v[92:95], v[152:155], v[206:209], v[92:95]
	v_mfma_f32_16x16x32_bf16 v[88:91], v[160:163], v[206:209], v[88:91]
	v_mfma_f32_16x16x32_bf16 v[76:79], v[152:155], v[214:217], v[76:79]
	v_mfma_f32_16x16x32_bf16 v[72:75], v[160:163], v[214:217], v[72:75]
	s_setprio 0
	s_setprio 1
	v_mfma_f32_16x16x32_bf16 v[116:119], v[164:167], v[186:189], v[116:119]
	v_mfma_f32_16x16x32_bf16 v[112:115], v[178:181], v[186:189], v[112:115]
	v_mfma_f32_16x16x32_bf16 v[100:103], v[164:167], v[194:197], v[100:103]
	v_mfma_f32_16x16x32_bf16 v[96:99], v[178:181], v[194:197], v[96:99]
	v_mfma_f32_16x16x32_bf16 v[84:87], v[164:167], v[202:205], v[84:87]
	v_mfma_f32_16x16x32_bf16 v[80:83], v[178:181], v[202:205], v[80:83]
	v_mfma_f32_16x16x32_bf16 v[68:71], v[164:167], v[210:213], v[68:71]
	v_mfma_f32_16x16x32_bf16 v[64:67], v[178:181], v[210:213], v[64:67]
	v_mfma_f32_16x16x32_bf16 v[116:119], v[168:171], v[190:193], v[116:119]
	v_mfma_f32_16x16x32_bf16 v[112:115], v[182:185], v[190:193], v[112:115]
	v_mfma_f32_16x16x32_bf16 v[100:103], v[168:171], v[198:201], v[100:103]
	v_mfma_f32_16x16x32_bf16 v[96:99], v[182:185], v[198:201], v[96:99]
	v_mfma_f32_16x16x32_bf16 v[84:87], v[168:171], v[206:209], v[84:87]
	v_mfma_f32_16x16x32_bf16 v[80:83], v[182:185], v[206:209], v[80:83]
	v_mfma_f32_16x16x32_bf16 v[68:71], v[168:171], v[214:217], v[68:71]
	v_mfma_f32_16x16x32_bf16 v[64:67], v[182:185], v[214:217], v[64:67]
	s_setprio 0
	s_barrier
	s_add_i32 s27, s64, s50
	v_lshl_add_u64 v[218:219], s[44:45], 0, v[130:131]
	s_mov_b32 m0, s27
	ds_read_b128 v[186:189], v177 offset:16384
	ds_read_b128 v[190:193], v177 offset:17408
	ds_read_b128 v[194:197], v177 offset:18432
	ds_read_b128 v[198:201], v177 offset:19456
	ds_read_b128 v[202:205], v177 offset:20480
	ds_read_b128 v[206:209], v177 offset:21504
	ds_read_b128 v[210:213], v177 offset:22528
	ds_read_b128 v[214:217], v177 offset:23552
	global_load_lds_dwordx4 v[218:219], off
	s_add_i32 m0, s27, 0x2000
	s_add_u32 s34, s44, 0x40000
	v_lshl_add_u64 v[220:221], s[44:45], 0, v[134:135]
	s_addc_u32 s35, s45, 0
	s_add_i32 s27, s65, s50
	global_load_lds_dwordx4 v[220:221], off
	s_waitcnt vmcnt(4)
	s_waitcnt lgkmcnt(0)
	s_barrier
	s_setprio 1
	s_waitcnt lgkmcnt(0)
	v_mfma_f32_16x16x32_bf16 v[60:63], v[148:151], v[186:189], v[60:63]
	v_mfma_f32_16x16x32_bf16 v[56:59], v[156:159], v[186:189], v[56:59]
	v_mfma_f32_16x16x32_bf16 v[44:47], v[148:151], v[194:197], v[44:47]
	v_mfma_f32_16x16x32_bf16 v[40:43], v[156:159], v[194:197], v[40:43]
	v_lshl_add_u64 v[222:223], s[34:35], 0, v[130:131]
	s_mov_b32 m0, s27
	v_lshl_add_u64 v[224:225], s[46:47], 0, v[132:133]
	global_load_lds_dwordx4 v[222:223], off
	v_mfma_f32_16x16x32_bf16 v[28:31], v[148:151], v[202:205], v[28:31]
	v_mfma_f32_16x16x32_bf16 v[24:27], v[156:159], v[202:205], v[24:27]
	v_mfma_f32_16x16x32_bf16 v[12:15], v[148:151], v[210:213], v[12:15]
	v_mfma_f32_16x16x32_bf16 v[8:11], v[156:159], v[210:213], v[8:11]
	v_mfma_f32_16x16x32_bf16 v[60:63], v[152:155], v[190:193], v[60:63]
	v_mfma_f32_16x16x32_bf16 v[56:59], v[160:163], v[190:193], v[56:59]
	v_lshl_add_u64 v[222:223], s[34:35], 0, v[134:135]
	s_add_i32 m0, s27, 0x2000
	s_nop 0
	global_load_lds_dwordx4 v[222:223], off
	v_mfma_f32_16x16x32_bf16 v[44:47], v[152:155], v[198:201], v[44:47]
	v_mfma_f32_16x16x32_bf16 v[40:43], v[160:163], v[198:201], v[40:43]
	v_mfma_f32_16x16x32_bf16 v[28:31], v[152:155], v[206:209], v[28:31]
	v_mfma_f32_16x16x32_bf16 v[24:27], v[160:163], v[206:209], v[24:27]
	v_mfma_f32_16x16x32_bf16 v[12:15], v[152:155], v[214:217], v[12:15]
	v_mfma_f32_16x16x32_bf16 v[8:11], v[160:163], v[214:217], v[8:11]
	s_setprio 0
	s_setprio 1
	v_mfma_f32_16x16x32_bf16 v[52:55], v[164:167], v[186:189], v[52:55]
	v_mfma_f32_16x16x32_bf16 v[48:51], v[178:181], v[186:189], v[48:51]
	v_lshl_add_u64 v[222:223], s[46:47], 0, v[128:129]
	s_mov_b32 m0, s51
	s_nop 0
	global_load_lds_dwordx4 v[222:223], off
	v_mfma_f32_16x16x32_bf16 v[36:39], v[164:167], v[194:197], v[36:39]
	v_mfma_f32_16x16x32_bf16 v[32:35], v[178:181], v[194:197], v[32:35]
	v_mfma_f32_16x16x32_bf16 v[20:23], v[164:167], v[202:205], v[20:23]
	v_mfma_f32_16x16x32_bf16 v[16:19], v[178:181], v[202:205], v[16:19]
	v_mfma_f32_16x16x32_bf16 v[4:7], v[164:167], v[210:213], v[4:7]
	v_mfma_f32_16x16x32_bf16 v[0:3], v[178:181], v[210:213], v[0:3]
	s_mov_b32 m0, s52
	s_nop 0
	global_load_lds_dwordx4 v[224:225], off
	v_mfma_f32_16x16x32_bf16 v[52:55], v[168:171], v[190:193], v[52:55]
	v_mfma_f32_16x16x32_bf16 v[48:51], v[182:185], v[190:193], v[48:51]
	v_mfma_f32_16x16x32_bf16 v[36:39], v[168:171], v[198:201], v[36:39]
	v_mfma_f32_16x16x32_bf16 v[32:35], v[182:185], v[198:201], v[32:35]
	v_mfma_f32_16x16x32_bf16 v[20:23], v[168:171], v[206:209], v[20:23]
	v_mfma_f32_16x16x32_bf16 v[16:19], v[182:185], v[206:209], v[16:19]
	v_mfma_f32_16x16x32_bf16 v[4:7], v[168:171], v[214:217], v[4:7]
	v_mfma_f32_16x16x32_bf16 v[0:3], v[182:185], v[214:217], v[0:3]
	s_setprio 0
	s_barrier
	s_add_i32 s27, 0, 0x18000
	v_add_u32_e32 v136, s27, v173
	s_add_i32 s30, 0, 0x1c000
	ds_read_b128 v[148:151], v136
	ds_read_b128 v[152:155], v136 offset:1024
	ds_read_b128 v[156:159], v136 offset:2048
	ds_read_b128 v[160:163], v136 offset:3072
	v_add_u32_e32 v136, s30, v173
	ds_read_b128 v[164:167], v136
	ds_read_b128 v[168:171], v136 offset:1024
	ds_read_b128 v[178:181], v136 offset:2048
	ds_read_b128 v[182:185], v136 offset:3072
	s_add_u32 s34, s46, 0x40000
	s_addc_u32 s35, s47, 0
	s_mov_b32 m0, s53
	v_lshl_add_u64 v[226:227], s[34:35], 0, v[128:129]
	ds_read_b128 v[186:189], v177 offset:32768
	ds_read_b128 v[190:193], v177 offset:33792
	ds_read_b128 v[194:197], v177 offset:34816
	ds_read_b128 v[198:201], v177 offset:35840
	ds_read_b128 v[202:205], v177 offset:36864
	ds_read_b128 v[206:209], v177 offset:37888
	ds_read_b128 v[210:213], v177 offset:38912
	ds_read_b128 v[214:217], v177 offset:39936
	global_load_lds_dwordx4 v[226:227], off
	v_lshl_add_u64 v[226:227], s[34:35], 0, v[132:133]
	s_mov_b32 m0, s54
	s_nop 0
	global_load_lds_dwordx4 v[226:227], off
	s_waitcnt vmcnt(8)
	s_waitcnt lgkmcnt(0)
	s_barrier
	s_setprio 1
	s_waitcnt lgkmcnt(0)
	v_mfma_f32_16x16x32_bf16 v[124:127], v[148:151], v[186:189], v[124:127]
	v_mfma_f32_16x16x32_bf16 v[120:123], v[156:159], v[186:189], v[120:123]
	v_mfma_f32_16x16x32_bf16 v[108:111], v[148:151], v[194:197], v[108:111]
	v_mfma_f32_16x16x32_bf16 v[104:107], v[156:159], v[194:197], v[104:107]
	v_mfma_f32_16x16x32_bf16 v[92:95], v[148:151], v[202:205], v[92:95]
	v_mfma_f32_16x16x32_bf16 v[88:91], v[156:159], v[202:205], v[88:91]
	v_mfma_f32_16x16x32_bf16 v[76:79], v[148:151], v[210:213], v[76:79]
	v_mfma_f32_16x16x32_bf16 v[72:75], v[156:159], v[210:213], v[72:75]
	v_mfma_f32_16x16x32_bf16 v[124:127], v[152:155], v[190:193], v[124:127]
	v_mfma_f32_16x16x32_bf16 v[120:123], v[160:163], v[190:193], v[120:123]
	v_mfma_f32_16x16x32_bf16 v[108:111], v[152:155], v[198:201], v[108:111]
	v_mfma_f32_16x16x32_bf16 v[104:107], v[160:163], v[198:201], v[104:107]
	v_mfma_f32_16x16x32_bf16 v[92:95], v[152:155], v[206:209], v[92:95]
	v_mfma_f32_16x16x32_bf16 v[88:91], v[160:163], v[206:209], v[88:91]
	v_mfma_f32_16x16x32_bf16 v[76:79], v[152:155], v[214:217], v[76:79]
	v_mfma_f32_16x16x32_bf16 v[72:75], v[160:163], v[214:217], v[72:75]
	s_setprio 0
	s_setprio 1
	v_mfma_f32_16x16x32_bf16 v[116:119], v[164:167], v[186:189], v[116:119]
	v_mfma_f32_16x16x32_bf16 v[112:115], v[178:181], v[186:189], v[112:115]
	v_mfma_f32_16x16x32_bf16 v[100:103], v[164:167], v[194:197], v[100:103]
	v_mfma_f32_16x16x32_bf16 v[96:99], v[178:181], v[194:197], v[96:99]
	v_mfma_f32_16x16x32_bf16 v[84:87], v[164:167], v[202:205], v[84:87]
	v_mfma_f32_16x16x32_bf16 v[80:83], v[178:181], v[202:205], v[80:83]
	v_mfma_f32_16x16x32_bf16 v[68:71], v[164:167], v[210:213], v[68:71]
	v_mfma_f32_16x16x32_bf16 v[64:67], v[178:181], v[210:213], v[64:67]
	v_mfma_f32_16x16x32_bf16 v[116:119], v[168:171], v[190:193], v[116:119]
	v_mfma_f32_16x16x32_bf16 v[112:115], v[182:185], v[190:193], v[112:115]
	v_mfma_f32_16x16x32_bf16 v[100:103], v[168:171], v[198:201], v[100:103]
	v_mfma_f32_16x16x32_bf16 v[96:99], v[182:185], v[198:201], v[96:99]
	v_mfma_f32_16x16x32_bf16 v[84:87], v[168:171], v[206:209], v[84:87]
	v_mfma_f32_16x16x32_bf16 v[80:83], v[182:185], v[206:209], v[80:83]
	v_mfma_f32_16x16x32_bf16 v[68:71], v[168:171], v[214:217], v[68:71]
	v_mfma_f32_16x16x32_bf16 v[64:67], v[182:185], v[214:217], v[64:67]
	s_setprio 0
	s_barrier
	s_add_i32 s27, s27, s50
	v_lshl_add_u64 v[218:219], v[218:219], 0, s[20:21]
	s_mov_b32 m0, s27
	ds_read_b128 v[186:189], v177 offset:49152
	ds_read_b128 v[190:193], v177 offset:50176
	ds_read_b128 v[194:197], v177 offset:51200
	ds_read_b128 v[198:201], v177 offset:52224
	ds_read_b128 v[202:205], v177 offset:53248
	ds_read_b128 v[206:209], v177 offset:54272
	ds_read_b128 v[210:213], v177 offset:55296
	ds_read_b128 v[214:217], v177 offset:56320
	global_load_lds_dwordx4 v[218:219], off
	s_add_i32 m0, s27, 0x2000
	s_add_u32 s34, s44, 0x40080
	v_lshl_add_u64 v[218:219], v[220:221], 0, s[20:21]
	s_addc_u32 s35, s45, 0
	s_add_i32 s27, s30, s50
	global_load_lds_dwordx4 v[218:219], off
	s_waitcnt vmcnt(4)
	s_waitcnt lgkmcnt(0)
	s_barrier
	s_setprio 1
	s_waitcnt lgkmcnt(0)
	v_mfma_f32_16x16x32_bf16 v[60:63], v[148:151], v[186:189], v[60:63]
	v_mfma_f32_16x16x32_bf16 v[56:59], v[156:159], v[186:189], v[56:59]
	v_mfma_f32_16x16x32_bf16 v[44:47], v[148:151], v[194:197], v[44:47]
	v_mfma_f32_16x16x32_bf16 v[40:43], v[156:159], v[194:197], v[40:43]
	v_lshl_add_u64 v[218:219], s[34:35], 0, v[130:131]
	s_mov_b32 m0, s27
	s_nop 0
	global_load_lds_dwordx4 v[218:219], off
	v_mfma_f32_16x16x32_bf16 v[28:31], v[148:151], v[202:205], v[28:31]
	v_mfma_f32_16x16x32_bf16 v[24:27], v[156:159], v[202:205], v[24:27]
	v_mfma_f32_16x16x32_bf16 v[12:15], v[148:151], v[210:213], v[12:15]
	v_mfma_f32_16x16x32_bf16 v[8:11], v[156:159], v[210:213], v[8:11]
	v_mfma_f32_16x16x32_bf16 v[60:63], v[152:155], v[190:193], v[60:63]
	v_mfma_f32_16x16x32_bf16 v[56:59], v[160:163], v[190:193], v[56:59]
	v_lshl_add_u64 v[218:219], s[34:35], 0, v[134:135]
	s_add_i32 m0, s27, 0x2000
	s_nop 0
	global_load_lds_dwordx4 v[218:219], off
	v_mfma_f32_16x16x32_bf16 v[44:47], v[152:155], v[198:201], v[44:47]
	v_mfma_f32_16x16x32_bf16 v[40:43], v[160:163], v[198:201], v[40:43]
	v_mfma_f32_16x16x32_bf16 v[28:31], v[152:155], v[206:209], v[28:31]
	v_mfma_f32_16x16x32_bf16 v[24:27], v[160:163], v[206:209], v[24:27]
	v_mfma_f32_16x16x32_bf16 v[12:15], v[152:155], v[214:217], v[12:15]
	v_mfma_f32_16x16x32_bf16 v[8:11], v[160:163], v[214:217], v[8:11]
	s_setprio 0
	s_setprio 1
	v_mfma_f32_16x16x32_bf16 v[52:55], v[164:167], v[186:189], v[52:55]
	v_mfma_f32_16x16x32_bf16 v[48:51], v[178:181], v[186:189], v[48:51]
	v_lshl_add_u64 v[218:219], v[222:223], 0, s[20:21]
	s_mov_b32 m0, s62
	s_nop 0
	global_load_lds_dwordx4 v[218:219], off
	v_mfma_f32_16x16x32_bf16 v[36:39], v[164:167], v[194:197], v[36:39]
	v_mfma_f32_16x16x32_bf16 v[32:35], v[178:181], v[194:197], v[32:35]
	v_mfma_f32_16x16x32_bf16 v[20:23], v[164:167], v[202:205], v[20:23]
	v_mfma_f32_16x16x32_bf16 v[16:19], v[178:181], v[202:205], v[16:19]
	v_mfma_f32_16x16x32_bf16 v[4:7], v[164:167], v[210:213], v[4:7]
	v_mfma_f32_16x16x32_bf16 v[0:3], v[178:181], v[210:213], v[0:3]
	v_lshl_add_u64 v[218:219], v[224:225], 0, s[20:21]
	s_mov_b32 m0, s63
	s_nop 0
	global_load_lds_dwordx4 v[218:219], off
	v_mfma_f32_16x16x32_bf16 v[52:55], v[168:171], v[190:193], v[52:55]
	v_mfma_f32_16x16x32_bf16 v[48:51], v[182:185], v[190:193], v[48:51]
	v_mfma_f32_16x16x32_bf16 v[36:39], v[168:171], v[198:201], v[36:39]
	v_mfma_f32_16x16x32_bf16 v[32:35], v[182:185], v[198:201], v[32:35]
	v_mfma_f32_16x16x32_bf16 v[20:23], v[168:171], v[206:209], v[20:23]
	v_mfma_f32_16x16x32_bf16 v[16:19], v[182:185], v[206:209], v[16:19]
	v_mfma_f32_16x16x32_bf16 v[4:7], v[168:171], v[214:217], v[4:7]
	v_mfma_f32_16x16x32_bf16 v[0:3], v[182:185], v[214:217], v[0:3]
	s_setprio 0
	s_barrier
	s_add_i32 s25, s25, 2
	s_add_u32 s42, s42, 0x100
	s_addc_u32 s43, s43, 0
	s_add_u32 s23, s23, 0x100
	s_addc_u32 s24, s24, 0
	s_cmp_gt_u32 s25, 13
	s_cbranch_scc0 .LBB5_248
	s_nop 0
	s_nop 0
	s_nop 0
	s_nop 0
	s_nop 0
	s_nop 0
	s_nop 0
	s_nop 0
	s_nop 0
	s_nop 0
	s_nop 0
	s_nop 0
	s_nop 0
	s_nop 0
	s_and_b64 vcc, exec, s[18:19]
	s_cbranch_vccz .LBB5_251
	s_barrier

.Lskw_P3:
	s_waitcnt lgkmcnt(0)
	s_barrier
	s_setprio 1
	s_waitcnt lgkmcnt(0)
	v_mfma_f32_16x16x32_bf16 v[156:159], v[64:67], v[160:163], v[156:159]
	v_mfma_f32_16x16x32_bf16 v[152:155], v[72:75], v[160:163], v[152:155]
	v_mfma_f32_16x16x32_bf16 v[124:127], v[64:67], v[168:171], v[124:127]
	v_mfma_f32_16x16x32_bf16 v[120:123], v[72:75], v[168:171], v[120:123]
	v_mfma_f32_16x16x32_bf16 v[108:111], v[64:67], v[176:179], v[108:111]
	v_mfma_f32_16x16x32_bf16 v[104:107], v[72:75], v[176:179], v[104:107]
	v_mfma_f32_16x16x32_bf16 v[92:95], v[64:67], v[184:187], v[92:95]
	v_mfma_f32_16x16x32_bf16 v[88:91], v[72:75], v[184:187], v[88:91]
	v_mfma_f32_16x16x32_bf16 v[156:159], v[68:71], v[164:167], v[156:159]
	v_mfma_f32_16x16x32_bf16 v[152:155], v[76:79], v[164:167], v[152:155]
	v_mfma_f32_16x16x32_bf16 v[124:127], v[68:71], v[172:175], v[124:127]
	v_mfma_f32_16x16x32_bf16 v[120:123], v[76:79], v[172:175], v[120:123]
	v_mfma_f32_16x16x32_bf16 v[108:111], v[68:71], v[180:183], v[108:111]
	v_mfma_f32_16x16x32_bf16 v[104:107], v[76:79], v[180:183], v[104:107]
	v_mfma_f32_16x16x32_bf16 v[92:95], v[68:71], v[188:191], v[92:95]
	v_mfma_f32_16x16x32_bf16 v[88:91], v[76:79], v[188:191], v[88:91]
	s_setprio 0
	s_setprio 1
	v_mfma_f32_16x16x32_bf16 v[132:135], v[136:139], v[160:163], v[132:135]
	v_mfma_f32_16x16x32_bf16 v[128:131], v[144:147], v[160:163], v[128:131]
	v_mfma_f32_16x16x32_bf16 v[116:119], v[136:139], v[168:171], v[116:119]
	v_mfma_f32_16x16x32_bf16 v[112:115], v[144:147], v[168:171], v[112:115]
	v_mfma_f32_16x16x32_bf16 v[100:103], v[136:139], v[176:179], v[100:103]
	v_mfma_f32_16x16x32_bf16 v[96:99], v[144:147], v[176:179], v[96:99]
	v_mfma_f32_16x16x32_bf16 v[84:87], v[136:139], v[184:187], v[84:87]
	v_mfma_f32_16x16x32_bf16 v[80:83], v[144:147], v[184:187], v[80:83]
	v_mfma_f32_16x16x32_bf16 v[132:135], v[140:143], v[164:167], v[132:135]
	v_mfma_f32_16x16x32_bf16 v[128:131], v[148:151], v[164:167], v[128:131]
	v_mfma_f32_16x16x32_bf16 v[116:119], v[140:143], v[172:175], v[116:119]
	v_mfma_f32_16x16x32_bf16 v[112:115], v[148:151], v[172:175], v[112:115]
	v_mfma_f32_16x16x32_bf16 v[100:103], v[140:143], v[180:183], v[100:103]
	v_mfma_f32_16x16x32_bf16 v[96:99], v[148:151], v[180:183], v[96:99]
	v_mfma_f32_16x16x32_bf16 v[84:87], v[140:143], v[188:191], v[84:87]
	v_mfma_f32_16x16x32_bf16 v[80:83], v[148:151], v[188:191], v[80:83]
	s_setprio 0
	s_barrier
	s_add_i32 s35, s55, s46
	v_lshl_add_u64 v[192:193], s[42:43], 0, v[202:203]
	s_mov_b32 m0, s35
	ds_read_b128 v[160:163], v231 offset:16384
	ds_read_b128 v[164:167], v231 offset:17408
	ds_read_b128 v[168:171], v231 offset:18432
	ds_read_b128 v[172:175], v231 offset:19456
	ds_read_b128 v[176:179], v231 offset:20480
	ds_read_b128 v[180:183], v231 offset:21504
	ds_read_b128 v[184:187], v231 offset:22528
	ds_read_b128 v[188:191], v231 offset:23552
	global_load_lds_dwordx4 v[192:193], off
	s_add_i32 m0, s35, 0x2000
	s_add_u32 s58, s42, 0x40000
	v_lshl_add_u64 v[194:195], s[42:43], 0, v[206:207]
	s_addc_u32 s59, s43, 0
	s_add_i32 s35, s56, s46
	global_load_lds_dwordx4 v[194:195], off
	s_waitcnt vmcnt(4)
	s_waitcnt lgkmcnt(0)
	s_barrier
	s_setprio 1
	s_waitcnt lgkmcnt(0)
	v_mfma_f32_16x16x32_bf16 v[60:63], v[64:67], v[160:163], v[60:63]
	v_mfma_f32_16x16x32_bf16 v[56:59], v[72:75], v[160:163], v[56:59]
	v_mfma_f32_16x16x32_bf16 v[44:47], v[64:67], v[168:171], v[44:47]
	v_mfma_f32_16x16x32_bf16 v[40:43], v[72:75], v[168:171], v[40:43]
	v_lshl_add_u64 v[196:197], s[58:59], 0, v[202:203]
	s_mov_b32 m0, s35
	v_lshl_add_u64 v[198:199], s[44:45], 0, v[204:205]
	global_load_lds_dwordx4 v[196:197], off
	v_mfma_f32_16x16x32_bf16 v[28:31], v[64:67], v[176:179], v[28:31]
	v_mfma_f32_16x16x32_bf16 v[24:27], v[72:75], v[176:179], v[24:27]
	v_mfma_f32_16x16x32_bf16 v[12:15], v[64:67], v[184:187], v[12:15]
	v_mfma_f32_16x16x32_bf16 v[8:11], v[72:75], v[184:187], v[8:11]
	v_mfma_f32_16x16x32_bf16 v[60:63], v[68:71], v[164:167], v[60:63]
	v_mfma_f32_16x16x32_bf16 v[56:59], v[76:79], v[164:167], v[56:59]
	v_lshl_add_u64 v[196:197], s[58:59], 0, v[206:207]
	s_add_i32 m0, s35, 0x2000
	s_nop 0
	global_load_lds_dwordx4 v[196:197], off
	v_mfma_f32_16x16x32_bf16 v[44:47], v[68:71], v[172:175], v[44:47]
	v_mfma_f32_16x16x32_bf16 v[40:43], v[76:79], v[172:175], v[40:43]
	v_mfma_f32_16x16x32_bf16 v[28:31], v[68:71], v[180:183], v[28:31]
	v_mfma_f32_16x16x32_bf16 v[24:27], v[76:79], v[180:183], v[24:27]
	v_mfma_f32_16x16x32_bf16 v[12:15], v[68:71], v[188:191], v[12:15]
	v_mfma_f32_16x16x32_bf16 v[8:11], v[76:79], v[188:191], v[8:11]
	s_setprio 0
	s_setprio 1
	v_mfma_f32_16x16x32_bf16 v[52:55], v[136:139], v[160:163], v[52:55]
	v_mfma_f32_16x16x32_bf16 v[48:51], v[144:147], v[160:163], v[48:51]
	v_lshl_add_u64 v[196:197], s[44:45], 0, v[200:201]
	s_mov_b32 m0, s39
	s_nop 0
	global_load_lds_dwordx4 v[196:197], off
	v_mfma_f32_16x16x32_bf16 v[36:39], v[136:139], v[168:171], v[36:39]
	v_mfma_f32_16x16x32_bf16 v[32:35], v[144:147], v[168:171], v[32:35]
	v_mfma_f32_16x16x32_bf16 v[20:23], v[136:139], v[176:179], v[20:23]
	v_mfma_f32_16x16x32_bf16 v[16:19], v[144:147], v[176:179], v[16:19]
	v_mfma_f32_16x16x32_bf16 v[4:7], v[136:139], v[184:187], v[4:7]
	v_mfma_f32_16x16x32_bf16 v[0:3], v[144:147], v[184:187], v[0:3]
	s_mov_b32 m0, s48
	s_nop 0
	global_load_lds_dwordx4 v[198:199], off
	v_mfma_f32_16x16x32_bf16 v[52:55], v[140:143], v[164:167], v[52:55]
	v_mfma_f32_16x16x32_bf16 v[48:51], v[148:151], v[164:167], v[48:51]
	v_mfma_f32_16x16x32_bf16 v[36:39], v[140:143], v[172:175], v[36:39]
	v_mfma_f32_16x16x32_bf16 v[32:35], v[148:151], v[172:175], v[32:35]
	v_mfma_f32_16x16x32_bf16 v[20:23], v[140:143], v[180:183], v[20:23]
	v_mfma_f32_16x16x32_bf16 v[16:19], v[148:151], v[180:183], v[16:19]
	v_mfma_f32_16x16x32_bf16 v[4:7], v[140:143], v[188:191], v[4:7]
	v_mfma_f32_16x16x32_bf16 v[0:3], v[148:151], v[188:191], v[0:3]
	s_setprio 0
	s_barrier
	s_add_i32 s35, 0, 0x18000
	s_add_i32 s57, 0, 0x1c000
	v_add_u32_e32 v76, s35, v227
	v_add_u32_e32 v148, s57, v227
	ds_read_b128 v[64:67], v76
	ds_read_b128 v[68:71], v76 offset:1024
	ds_read_b128 v[72:75], v76 offset:2048
	ds_read_b128 v[76:79], v76 offset:3072
	ds_read_b128 v[136:139], v148
	ds_read_b128 v[140:143], v148 offset:1024
	ds_read_b128 v[144:147], v148 offset:2048
	ds_read_b128 v[148:151], v148 offset:3072
	s_add_u32 s44, s44, 0x40000
	s_addc_u32 s45, s45, 0
	s_mov_b32 m0, s49
	v_lshl_add_u64 v[216:217], s[44:45], 0, v[200:201]
	ds_read_b128 v[160:163], v231 offset:32768
	ds_read_b128 v[164:167], v231 offset:33792
	ds_read_b128 v[168:171], v231 offset:34816
	ds_read_b128 v[172:175], v231 offset:35840
	ds_read_b128 v[176:179], v231 offset:36864
	ds_read_b128 v[180:183], v231 offset:37888
	ds_read_b128 v[184:187], v231 offset:38912
	ds_read_b128 v[188:191], v231 offset:39936
	global_load_lds_dwordx4 v[216:217], off
	v_lshl_add_u64 v[216:217], s[44:45], 0, v[204:205]
	s_mov_b32 m0, s50
	s_nop 0
	global_load_lds_dwordx4 v[216:217], off
	s_waitcnt vmcnt(8)
	s_waitcnt lgkmcnt(0)
	s_barrier
	s_setprio 1
	s_waitcnt lgkmcnt(0)
	v_mfma_f32_16x16x32_bf16 v[156:159], v[64:67], v[160:163], v[156:159]
	v_mfma_f32_16x16x32_bf16 v[152:155], v[72:75], v[160:163], v[152:155]
	v_mfma_f32_16x16x32_bf16 v[124:127], v[64:67], v[168:171], v[124:127]
	v_mfma_f32_16x16x32_bf16 v[120:123], v[72:75], v[168:171], v[120:123]
	v_mfma_f32_16x16x32_bf16 v[108:111], v[64:67], v[176:179], v[108:111]
	v_mfma_f32_16x16x32_bf16 v[104:107], v[72:75], v[176:179], v[104:107]
	v_mfma_f32_16x16x32_bf16 v[92:95], v[64:67], v[184:187], v[92:95]
	v_mfma_f32_16x16x32_bf16 v[88:91], v[72:75], v[184:187], v[88:91]
	v_mfma_f32_16x16x32_bf16 v[156:159], v[68:71], v[164:167], v[156:159]
	v_mfma_f32_16x16x32_bf16 v[152:155], v[76:79], v[164:167], v[152:155]
	v_mfma_f32_16x16x32_bf16 v[124:127], v[68:71], v[172:175], v[124:127]
	v_mfma_f32_16x16x32_bf16 v[120:123], v[76:79], v[172:175], v[120:123]
	v_mfma_f32_16x16x32_bf16 v[108:111], v[68:71], v[180:183], v[108:111]
	v_mfma_f32_16x16x32_bf16 v[104:107], v[76:79], v[180:183], v[104:107]
	v_mfma_f32_16x16x32_bf16 v[92:95], v[68:71], v[188:191], v[92:95]
	v_mfma_f32_16x16x32_bf16 v[88:91], v[76:79], v[188:191], v[88:91]
	s_setprio 0
	s_setprio 1
	v_mfma_f32_16x16x32_bf16 v[132:135], v[136:139], v[160:163], v[132:135]
	v_mfma_f32_16x16x32_bf16 v[128:131], v[144:147], v[160:163], v[128:131]
	v_mfma_f32_16x16x32_bf16 v[116:119], v[136:139], v[168:171], v[116:119]
	v_mfma_f32_16x16x32_bf16 v[112:115], v[144:147], v[168:171], v[112:115]
	v_mfma_f32_16x16x32_bf16 v[100:103], v[136:139], v[176:179], v[100:103]
	v_mfma_f32_16x16x32_bf16 v[96:99], v[144:147], v[176:179], v[96:99]
	v_mfma_f32_16x16x32_bf16 v[84:87], v[136:139], v[184:187], v[84:87]
	v_mfma_f32_16x16x32_bf16 v[80:83], v[144:147], v[184:187], v[80:83]
	v_mfma_f32_16x16x32_bf16 v[132:135], v[140:143], v[164:167], v[132:135]
	v_mfma_f32_16x16x32_bf16 v[128:131], v[148:151], v[164:167], v[128:131]
	v_mfma_f32_16x16x32_bf16 v[116:119], v[140:143], v[172:175], v[116:119]
	v_mfma_f32_16x16x32_bf16 v[112:115], v[148:151], v[172:175], v[112:115]
	v_mfma_f32_16x16x32_bf16 v[100:103], v[140:143], v[180:183], v[100:103]
	v_mfma_f32_16x16x32_bf16 v[96:99], v[148:151], v[180:183], v[96:99]
	v_mfma_f32_16x16x32_bf16 v[84:87], v[140:143], v[188:191], v[84:87]
	v_mfma_f32_16x16x32_bf16 v[80:83], v[148:151], v[188:191], v[80:83]
	s_setprio 0
	s_barrier
	s_add_i32 s35, s35, s46
	v_lshl_add_u64 v[192:193], v[192:193], 0, s[16:17]
	s_mov_b32 m0, s35
	ds_read_b128 v[160:163], v231 offset:49152
	ds_read_b128 v[164:167], v231 offset:50176
	ds_read_b128 v[168:171], v231 offset:51200
	ds_read_b128 v[172:175], v231 offset:52224
	ds_read_b128 v[176:179], v231 offset:53248
	ds_read_b128 v[180:183], v231 offset:54272
	ds_read_b128 v[184:187], v231 offset:55296
	ds_read_b128 v[188:191], v231 offset:56320
	global_load_lds_dwordx4 v[192:193], off
	s_add_i32 m0, s35, 0x2000
	s_add_u32 s42, s42, 0x40080
	v_lshl_add_u64 v[192:193], v[194:195], 0, s[16:17]
	s_addc_u32 s43, s43, 0
	s_add_i32 s35, s57, s46
	global_load_lds_dwordx4 v[192:193], off
	s_waitcnt vmcnt(4)
	s_waitcnt lgkmcnt(0)
	s_barrier
	s_setprio 1
	s_waitcnt lgkmcnt(0)
	v_mfma_f32_16x16x32_bf16 v[60:63], v[64:67], v[160:163], v[60:63]
	v_mfma_f32_16x16x32_bf16 v[56:59], v[72:75], v[160:163], v[56:59]
	v_mfma_f32_16x16x32_bf16 v[44:47], v[64:67], v[168:171], v[44:47]
	v_mfma_f32_16x16x32_bf16 v[40:43], v[72:75], v[168:171], v[40:43]
	v_lshl_add_u64 v[192:193], s[42:43], 0, v[202:203]
	s_mov_b32 m0, s35
	s_nop 0
	global_load_lds_dwordx4 v[192:193], off
	v_mfma_f32_16x16x32_bf16 v[28:31], v[64:67], v[176:179], v[28:31]
	v_mfma_f32_16x16x32_bf16 v[24:27], v[72:75], v[176:179], v[24:27]
	v_mfma_f32_16x16x32_bf16 v[12:15], v[64:67], v[184:187], v[12:15]
	v_mfma_f32_16x16x32_bf16 v[8:11], v[72:75], v[184:187], v[8:11]
	v_mfma_f32_16x16x32_bf16 v[60:63], v[68:71], v[164:167], v[60:63]
	v_mfma_f32_16x16x32_bf16 v[56:59], v[76:79], v[164:167], v[56:59]
	v_lshl_add_u64 v[192:193], s[42:43], 0, v[206:207]
	s_add_i32 m0, s35, 0x2000
	s_nop 0
	global_load_lds_dwordx4 v[192:193], off
	v_mfma_f32_16x16x32_bf16 v[44:47], v[68:71], v[172:175], v[44:47]
	v_mfma_f32_16x16x32_bf16 v[40:43], v[76:79], v[172:175], v[40:43]
	v_mfma_f32_16x16x32_bf16 v[28:31], v[68:71], v[180:183], v[28:31]
	v_mfma_f32_16x16x32_bf16 v[24:27], v[76:79], v[180:183], v[24:27]
	v_mfma_f32_16x16x32_bf16 v[12:15], v[68:71], v[188:191], v[12:15]
	v_mfma_f32_16x16x32_bf16 v[8:11], v[76:79], v[188:191], v[8:11]
	s_setprio 0
	s_setprio 1
	v_mfma_f32_16x16x32_bf16 v[52:55], v[136:139], v[160:163], v[52:55]
	v_mfma_f32_16x16x32_bf16 v[48:51], v[144:147], v[160:163], v[48:51]
	v_lshl_add_u64 v[192:193], v[196:197], 0, s[16:17]
	s_mov_b32 m0, s53
	s_nop 0
	global_load_lds_dwordx4 v[192:193], off
	v_mfma_f32_16x16x32_bf16 v[36:39], v[136:139], v[168:171], v[36:39]
	v_mfma_f32_16x16x32_bf16 v[32:35], v[144:147], v[168:171], v[32:35]
	v_mfma_f32_16x16x32_bf16 v[20:23], v[136:139], v[176:179], v[20:23]
	v_mfma_f32_16x16x32_bf16 v[16:19], v[144:147], v[176:179], v[16:19]
	v_mfma_f32_16x16x32_bf16 v[4:7], v[136:139], v[184:187], v[4:7]
	v_mfma_f32_16x16x32_bf16 v[0:3], v[144:147], v[184:187], v[0:3]
	v_lshl_add_u64 v[192:193], v[198:199], 0, s[16:17]
	s_mov_b32 m0, s54
	s_nop 0
	global_load_lds_dwordx4 v[192:193], off
	v_mfma_f32_16x16x32_bf16 v[52:55], v[140:143], v[164:167], v[52:55]
	v_mfma_f32_16x16x32_bf16 v[48:51], v[148:151], v[164:167], v[48:51]
	v_mfma_f32_16x16x32_bf16 v[36:39], v[140:143], v[172:175], v[36:39]
	v_mfma_f32_16x16x32_bf16 v[32:35], v[148:151], v[172:175], v[32:35]
	v_mfma_f32_16x16x32_bf16 v[20:23], v[140:143], v[180:183], v[20:23]
	v_mfma_f32_16x16x32_bf16 v[16:19], v[148:151], v[180:183], v[16:19]
	v_mfma_f32_16x16x32_bf16 v[4:7], v[140:143], v[188:191], v[4:7]
	v_mfma_f32_16x16x32_bf16 v[0:3], v[148:151], v[188:191], v[0:3]
	s_setprio 0
	s_barrier
	s_add_i32 s34, s34, 2
	s_add_u32 s40, s40, 0x100
	s_addc_u32 s41, s41, 0
	s_add_u32 s30, s30, 0x100
	s_addc_u32 s33, s33, 0
	s_cmp_gt_u32 s34, 13
	s_cbranch_scc0 .LBB5_463
	s_nop 0
	s_nop 0
	s_nop 0
	s_nop 0
	s_nop 0
	s_nop 0
	s_nop 0
	s_nop 0
	s_nop 0
	s_nop 0
	s_nop 0
	s_nop 0
	s_nop 0
	s_nop 0
	s_and_b64 vcc, exec, s[14:15]
	s_cbranch_vccz .LBB5_466
	s_barrier

.Lskw_P4:
	s_waitcnt lgkmcnt(0)
	s_barrier
	s_setprio 1
	s_waitcnt lgkmcnt(0)
	v_mfma_f32_16x16x32_bf16 v[124:127], v[128:131], v[160:163], v[124:127]
	v_mfma_f32_16x16x32_bf16 v[120:123], v[136:139], v[160:163], v[120:123]
	v_mfma_f32_16x16x32_bf16 v[108:111], v[128:131], v[168:171], v[108:111]
	v_mfma_f32_16x16x32_bf16 v[104:107], v[136:139], v[168:171], v[104:107]
	v_mfma_f32_16x16x32_bf16 v[92:95], v[128:131], v[192:195], v[92:95]
	v_mfma_f32_16x16x32_bf16 v[88:91], v[136:139], v[192:195], v[88:91]
	v_mfma_f32_16x16x32_bf16 v[76:79], v[128:131], v[200:203], v[76:79]
	v_mfma_f32_16x16x32_bf16 v[72:75], v[136:139], v[200:203], v[72:75]
	v_mfma_f32_16x16x32_bf16 v[124:127], v[132:135], v[164:167], v[124:127]
	v_mfma_f32_16x16x32_bf16 v[120:123], v[140:143], v[164:167], v[120:123]
	v_mfma_f32_16x16x32_bf16 v[108:111], v[132:135], v[172:175], v[108:111]
	v_mfma_f32_16x16x32_bf16 v[104:107], v[140:143], v[172:175], v[104:107]
	v_mfma_f32_16x16x32_bf16 v[92:95], v[132:135], v[196:199], v[92:95]
	v_mfma_f32_16x16x32_bf16 v[88:91], v[140:143], v[196:199], v[88:91]
	v_mfma_f32_16x16x32_bf16 v[76:79], v[132:135], v[212:215], v[76:79]
	v_mfma_f32_16x16x32_bf16 v[72:75], v[140:143], v[212:215], v[72:75]
	s_setprio 0
	s_setprio 1
	v_mfma_f32_16x16x32_bf16 v[116:119], v[144:147], v[160:163], v[116:119]
	v_mfma_f32_16x16x32_bf16 v[112:115], v[152:155], v[160:163], v[112:115]
	v_mfma_f32_16x16x32_bf16 v[100:103], v[144:147], v[168:171], v[100:103]
	v_mfma_f32_16x16x32_bf16 v[96:99], v[152:155], v[168:171], v[96:99]
	v_mfma_f32_16x16x32_bf16 v[84:87], v[144:147], v[192:195], v[84:87]
	v_mfma_f32_16x16x32_bf16 v[80:83], v[152:155], v[192:195], v[80:83]
	v_mfma_f32_16x16x32_bf16 v[68:71], v[144:147], v[200:203], v[68:71]
	v_mfma_f32_16x16x32_bf16 v[64:67], v[152:155], v[200:203], v[64:67]
	v_mfma_f32_16x16x32_bf16 v[116:119], v[148:151], v[164:167], v[116:119]
	v_mfma_f32_16x16x32_bf16 v[112:115], v[156:159], v[164:167], v[112:115]
	v_mfma_f32_16x16x32_bf16 v[100:103], v[148:151], v[172:175], v[100:103]
	v_mfma_f32_16x16x32_bf16 v[96:99], v[156:159], v[172:175], v[96:99]
	v_mfma_f32_16x16x32_bf16 v[84:87], v[148:151], v[196:199], v[84:87]
	v_mfma_f32_16x16x32_bf16 v[80:83], v[156:159], v[196:199], v[80:83]
	v_mfma_f32_16x16x32_bf16 v[68:71], v[148:151], v[212:215], v[68:71]
	v_mfma_f32_16x16x32_bf16 v[64:67], v[156:159], v[212:215], v[64:67]
	s_setprio 0
	s_barrier
	s_add_i32 s58, s51, s30
	v_lshl_add_u64 v[216:217], s[42:43], 0, v[178:179]
	s_mov_b32 m0, s58
	ds_read_b128 v[160:163], v211 offset:16384
	ds_read_b128 v[164:167], v211 offset:17408
	ds_read_b128 v[168:171], v211 offset:18432
	ds_read_b128 v[172:175], v211 offset:19456
	ds_read_b128 v[192:195], v211 offset:20480
	ds_read_b128 v[196:199], v211 offset:21504
	ds_read_b128 v[200:203], v211 offset:22528
	ds_read_b128 v[212:215], v211 offset:23552
	global_load_lds_dwordx4 v[216:217], off
	s_add_i32 m0, s58, 0x2000
	s_add_u32 s58, s42, 0x40000
	v_lshl_add_u64 v[218:219], s[42:43], 0, v[182:183]
	s_addc_u32 s59, s43, 0
	s_add_i32 s60, s52, s30
	global_load_lds_dwordx4 v[218:219], off
	s_waitcnt vmcnt(4)
	s_waitcnt lgkmcnt(0)
	s_barrier
	s_setprio 1
	s_waitcnt lgkmcnt(0)
	v_mfma_f32_16x16x32_bf16 v[60:63], v[128:131], v[160:163], v[60:63]
	v_mfma_f32_16x16x32_bf16 v[56:59], v[136:139], v[160:163], v[56:59]
	v_mfma_f32_16x16x32_bf16 v[44:47], v[128:131], v[168:171], v[44:47]
	v_mfma_f32_16x16x32_bf16 v[40:43], v[136:139], v[168:171], v[40:43]
	v_lshl_add_u64 v[220:221], s[58:59], 0, v[178:179]
	s_mov_b32 m0, s60
	v_lshl_add_u64 v[222:223], s[44:45], 0, v[180:181]
	global_load_lds_dwordx4 v[220:221], off
	v_mfma_f32_16x16x32_bf16 v[28:31], v[128:131], v[192:195], v[28:31]
	v_mfma_f32_16x16x32_bf16 v[24:27], v[136:139], v[192:195], v[24:27]
	v_mfma_f32_16x16x32_bf16 v[12:15], v[128:131], v[200:203], v[12:15]
	v_mfma_f32_16x16x32_bf16 v[8:11], v[136:139], v[200:203], v[8:11]
	v_mfma_f32_16x16x32_bf16 v[60:63], v[132:135], v[164:167], v[60:63]
	v_mfma_f32_16x16x32_bf16 v[56:59], v[140:143], v[164:167], v[56:59]
	v_lshl_add_u64 v[220:221], s[58:59], 0, v[182:183]
	s_add_i32 m0, s60, 0x2000
	s_nop 0
	global_load_lds_dwordx4 v[220:221], off
	v_mfma_f32_16x16x32_bf16 v[44:47], v[132:135], v[172:175], v[44:47]
	v_mfma_f32_16x16x32_bf16 v[40:43], v[140:143], v[172:175], v[40:43]
	v_mfma_f32_16x16x32_bf16 v[28:31], v[132:135], v[196:199], v[28:31]
	v_mfma_f32_16x16x32_bf16 v[24:27], v[140:143], v[196:199], v[24:27]
	v_mfma_f32_16x16x32_bf16 v[12:15], v[132:135], v[212:215], v[12:15]
	v_mfma_f32_16x16x32_bf16 v[8:11], v[140:143], v[212:215], v[8:11]
	s_setprio 0
	s_setprio 1
	v_mfma_f32_16x16x32_bf16 v[52:55], v[144:147], v[160:163], v[52:55]
	v_mfma_f32_16x16x32_bf16 v[48:51], v[152:155], v[160:163], v[48:51]
	v_lshl_add_u64 v[220:221], s[44:45], 0, v[176:177]
	s_mov_b32 m0, s31
	s_nop 0
	global_load_lds_dwordx4 v[220:221], off
	v_mfma_f32_16x16x32_bf16 v[36:39], v[144:147], v[168:171], v[36:39]
	v_mfma_f32_16x16x32_bf16 v[32:35], v[152:155], v[168:171], v[32:35]
	v_mfma_f32_16x16x32_bf16 v[20:23], v[144:147], v[192:195], v[20:23]
	v_mfma_f32_16x16x32_bf16 v[16:19], v[152:155], v[192:195], v[16:19]
	v_mfma_f32_16x16x32_bf16 v[4:7], v[144:147], v[200:203], v[4:7]
	v_mfma_f32_16x16x32_bf16 v[0:3], v[152:155], v[200:203], v[0:3]
	s_mov_b32 m0, s33
	s_nop 0
	global_load_lds_dwordx4 v[222:223], off
	v_mfma_f32_16x16x32_bf16 v[52:55], v[148:151], v[164:167], v[52:55]
	v_mfma_f32_16x16x32_bf16 v[48:51], v[156:159], v[164:167], v[48:51]
	v_mfma_f32_16x16x32_bf16 v[36:39], v[148:151], v[172:175], v[36:39]
	v_mfma_f32_16x16x32_bf16 v[32:35], v[156:159], v[172:175], v[32:35]
	v_mfma_f32_16x16x32_bf16 v[20:23], v[148:151], v[196:199], v[20:23]
	v_mfma_f32_16x16x32_bf16 v[16:19], v[156:159], v[196:199], v[16:19]
	v_mfma_f32_16x16x32_bf16 v[4:7], v[148:151], v[212:215], v[4:7]
	v_mfma_f32_16x16x32_bf16 v[0:3], v[156:159], v[212:215], v[0:3]
	s_setprio 0
	s_barrier
	s_add_i32 s58, 0, 0x18000
	s_add_i32 s59, 0, 0x1c000
	v_add_u32_e32 v140, s58, v205
	v_add_u32_e32 v156, s59, v205
	ds_read_b128 v[128:131], v140
	ds_read_b128 v[132:135], v140 offset:1024
	ds_read_b128 v[136:139], v140 offset:2048
	ds_read_b128 v[140:143], v140 offset:3072
	ds_read_b128 v[144:147], v156
	ds_read_b128 v[148:151], v156 offset:1024
	ds_read_b128 v[152:155], v156 offset:2048
	ds_read_b128 v[156:159], v156 offset:3072
	s_add_u32 s44, s44, 0x40000
	s_addc_u32 s45, s45, 0
	s_mov_b32 m0, s34
	v_lshl_add_u64 v[224:225], s[44:45], 0, v[176:177]
	ds_read_b128 v[160:163], v211 offset:32768
	ds_read_b128 v[164:167], v211 offset:33792
	ds_read_b128 v[168:171], v211 offset:34816
	ds_read_b128 v[172:175], v211 offset:35840
	ds_read_b128 v[192:195], v211 offset:36864
	ds_read_b128 v[196:199], v211 offset:37888
	ds_read_b128 v[200:203], v211 offset:38912
	ds_read_b128 v[212:215], v211 offset:39936
	global_load_lds_dwordx4 v[224:225], off
	v_lshl_add_u64 v[224:225], s[44:45], 0, v[180:181]
	s_mov_b32 m0, s35
	s_nop 0
	global_load_lds_dwordx4 v[224:225], off
	s_waitcnt vmcnt(8)
	s_waitcnt lgkmcnt(0)
	s_barrier
	s_setprio 1
	s_waitcnt lgkmcnt(0)
	v_mfma_f32_16x16x32_bf16 v[124:127], v[128:131], v[160:163], v[124:127]
	v_mfma_f32_16x16x32_bf16 v[120:123], v[136:139], v[160:163], v[120:123]
	v_mfma_f32_16x16x32_bf16 v[108:111], v[128:131], v[168:171], v[108:111]
	v_mfma_f32_16x16x32_bf16 v[104:107], v[136:139], v[168:171], v[104:107]
	v_mfma_f32_16x16x32_bf16 v[92:95], v[128:131], v[192:195], v[92:95]
	v_mfma_f32_16x16x32_bf16 v[88:91], v[136:139], v[192:195], v[88:91]
	v_mfma_f32_16x16x32_bf16 v[76:79], v[128:131], v[200:203], v[76:79]
	v_mfma_f32_16x16x32_bf16 v[72:75], v[136:139], v[200:203], v[72:75]
	v_mfma_f32_16x16x32_bf16 v[124:127], v[132:135], v[164:167], v[124:127]
	v_mfma_f32_16x16x32_bf16 v[120:123], v[140:143], v[164:167], v[120:123]
	v_mfma_f32_16x16x32_bf16 v[108:111], v[132:135], v[172:175], v[108:111]
	v_mfma_f32_16x16x32_bf16 v[104:107], v[140:143], v[172:175], v[104:107]
	v_mfma_f32_16x16x32_bf16 v[92:95], v[132:135], v[196:199], v[92:95]
	v_mfma_f32_16x16x32_bf16 v[88:91], v[140:143], v[196:199], v[88:91]
	v_mfma_f32_16x16x32_bf16 v[76:79], v[132:135], v[212:215], v[76:79]
	v_mfma_f32_16x16x32_bf16 v[72:75], v[140:143], v[212:215], v[72:75]
	s_setprio 0
	s_setprio 1
	v_mfma_f32_16x16x32_bf16 v[116:119], v[144:147], v[160:163], v[116:119]
	v_mfma_f32_16x16x32_bf16 v[112:115], v[152:155], v[160:163], v[112:115]
	v_mfma_f32_16x16x32_bf16 v[100:103], v[144:147], v[168:171], v[100:103]
	v_mfma_f32_16x16x32_bf16 v[96:99], v[152:155], v[168:171], v[96:99]
	v_mfma_f32_16x16x32_bf16 v[84:87], v[144:147], v[192:195], v[84:87]
	v_mfma_f32_16x16x32_bf16 v[80:83], v[152:155], v[192:195], v[80:83]
	v_mfma_f32_16x16x32_bf16 v[68:71], v[144:147], v[200:203], v[68:71]
	v_mfma_f32_16x16x32_bf16 v[64:67], v[152:155], v[200:203], v[64:67]
	v_mfma_f32_16x16x32_bf16 v[116:119], v[148:151], v[164:167], v[116:119]
	v_mfma_f32_16x16x32_bf16 v[112:115], v[156:159], v[164:167], v[112:115]
	v_mfma_f32_16x16x32_bf16 v[100:103], v[148:151], v[172:175], v[100:103]
	v_mfma_f32_16x16x32_bf16 v[96:99], v[156:159], v[172:175], v[96:99]
	v_mfma_f32_16x16x32_bf16 v[84:87], v[148:151], v[196:199], v[84:87]
	v_mfma_f32_16x16x32_bf16 v[80:83], v[156:159], v[196:199], v[80:83]
	v_mfma_f32_16x16x32_bf16 v[68:71], v[148:151], v[212:215], v[68:71]
	v_mfma_f32_16x16x32_bf16 v[64:67], v[156:159], v[212:215], v[64:67]
	s_setprio 0
	s_barrier
	s_add_i32 s44, s58, s30
	v_lshl_add_u64 v[216:217], v[216:217], 0, s[16:17]
	s_mov_b32 m0, s44
	ds_read_b128 v[160:163], v211 offset:49152
	ds_read_b128 v[164:167], v211 offset:50176
	ds_read_b128 v[168:171], v211 offset:51200
	ds_read_b128 v[172:175], v211 offset:52224
	ds_read_b128 v[192:195], v211 offset:53248
	ds_read_b128 v[196:199], v211 offset:54272
	ds_read_b128 v[200:203], v211 offset:55296
	ds_read_b128 v[212:215], v211 offset:56320
	global_load_lds_dwordx4 v[216:217], off
	s_add_i32 m0, s44, 0x2000
	s_add_u32 s42, s42, 0x40080
	v_lshl_add_u64 v[216:217], v[218:219], 0, s[16:17]
	s_addc_u32 s43, s43, 0
	s_add_i32 s44, s59, s30
	global_load_lds_dwordx4 v[216:217], off
	s_waitcnt vmcnt(4)
	s_waitcnt lgkmcnt(0)
	s_barrier
	s_setprio 1
	s_waitcnt lgkmcnt(0)
	v_mfma_f32_16x16x32_bf16 v[60:63], v[128:131], v[160:163], v[60:63]
	v_mfma_f32_16x16x32_bf16 v[56:59], v[136:139], v[160:163], v[56:59]
	v_mfma_f32_16x16x32_bf16 v[44:47], v[128:131], v[168:171], v[44:47]
	v_mfma_f32_16x16x32_bf16 v[40:43], v[136:139], v[168:171], v[40:43]
	v_lshl_add_u64 v[216:217], s[42:43], 0, v[178:179]
	s_mov_b32 m0, s44
	s_nop 0
	global_load_lds_dwordx4 v[216:217], off
	v_mfma_f32_16x16x32_bf16 v[28:31], v[128:131], v[192:195], v[28:31]
	v_mfma_f32_16x16x32_bf16 v[24:27], v[136:139], v[192:195], v[24:27]
	v_mfma_f32_16x16x32_bf16 v[12:15], v[128:131], v[200:203], v[12:15]
	v_mfma_f32_16x16x32_bf16 v[8:11], v[136:139], v[200:203], v[8:11]
	v_mfma_f32_16x16x32_bf16 v[60:63], v[132:135], v[164:167], v[60:63]
	v_mfma_f32_16x16x32_bf16 v[56:59], v[140:143], v[164:167], v[56:59]
	v_lshl_add_u64 v[216:217], s[42:43], 0, v[182:183]
	s_add_i32 m0, s44, 0x2000
	s_nop 0
	global_load_lds_dwordx4 v[216:217], off
	v_mfma_f32_16x16x32_bf16 v[44:47], v[132:135], v[172:175], v[44:47]
	v_mfma_f32_16x16x32_bf16 v[40:43], v[140:143], v[172:175], v[40:43]
	v_mfma_f32_16x16x32_bf16 v[28:31], v[132:135], v[196:199], v[28:31]
	v_mfma_f32_16x16x32_bf16 v[24:27], v[140:143], v[196:199], v[24:27]
	v_mfma_f32_16x16x32_bf16 v[12:15], v[132:135], v[212:215], v[12:15]
	v_mfma_f32_16x16x32_bf16 v[8:11], v[140:143], v[212:215], v[8:11]
	s_setprio 0
	s_setprio 1
	v_mfma_f32_16x16x32_bf16 v[52:55], v[144:147], v[160:163], v[52:55]
	v_mfma_f32_16x16x32_bf16 v[48:51], v[152:155], v[160:163], v[48:51]
	v_lshl_add_u64 v[216:217], v[220:221], 0, s[16:17]
	s_mov_b32 m0, s49
	s_nop 0
	global_load_lds_dwordx4 v[216:217], off
	v_mfma_f32_16x16x32_bf16 v[36:39], v[144:147], v[168:171], v[36:39]
	v_mfma_f32_16x16x32_bf16 v[32:35], v[152:155], v[168:171], v[32:35]
	v_mfma_f32_16x16x32_bf16 v[20:23], v[144:147], v[192:195], v[20:23]
	v_mfma_f32_16x16x32_bf16 v[16:19], v[152:155], v[192:195], v[16:19]
	v_mfma_f32_16x16x32_bf16 v[4:7], v[144:147], v[200:203], v[4:7]
	v_mfma_f32_16x16x32_bf16 v[0:3], v[152:155], v[200:203], v[0:3]
	v_lshl_add_u64 v[216:217], v[222:223], 0, s[16:17]
	s_mov_b32 m0, s50
	s_nop 0
	global_load_lds_dwordx4 v[216:217], off
	v_mfma_f32_16x16x32_bf16 v[52:55], v[148:151], v[164:167], v[52:55]
	v_mfma_f32_16x16x32_bf16 v[48:51], v[156:159], v[164:167], v[48:51]
	v_mfma_f32_16x16x32_bf16 v[36:39], v[148:151], v[172:175], v[36:39]
	v_mfma_f32_16x16x32_bf16 v[32:35], v[156:159], v[172:175], v[32:35]
	v_mfma_f32_16x16x32_bf16 v[20:23], v[148:151], v[196:199], v[20:23]
	v_mfma_f32_16x16x32_bf16 v[16:19], v[156:159], v[196:199], v[16:19]
	v_mfma_f32_16x16x32_bf16 v[4:7], v[148:151], v[212:215], v[4:7]
	v_mfma_f32_16x16x32_bf16 v[0:3], v[156:159], v[212:215], v[0:3]
	s_setprio 0
	s_barrier
	s_add_i32 s57, s57, 2
	s_add_u32 s40, s40, 0x100
	s_addc_u32 s41, s41, 0
	s_add_u32 s55, s55, 0x100
	s_addc_u32 s56, s56, 0
	s_cmp_gt_u32 s57, 13
	s_cbranch_scc0 .LBB5_536
	s_nop 0
	s_nop 0
	s_nop 0
	s_nop 0
	s_nop 0
	s_nop 0
	s_nop 0
	s_nop 0
	s_nop 0
	s_nop 0
	s_nop 0
	s_nop 0
	s_nop 0
	s_nop 0
	s_and_b64 vcc, exec, s[14:15]
	s_cbranch_vccz .LBB5_539
	s_barrier

.Lskw_P5:
	s_waitcnt lgkmcnt(0)
	s_barrier
	s_setprio 1
	s_waitcnt lgkmcnt(0)
	v_mfma_f32_16x16x32_bf16 v[140:143], v[32:35], v[192:195], v[140:143]
	v_mfma_f32_16x16x32_bf16 v[136:139], v[40:43], v[192:195], v[136:139]
	v_mfma_f32_16x16x32_bf16 v[124:127], v[32:35], v[200:203], v[124:127]
	v_mfma_f32_16x16x32_bf16 v[120:123], v[40:43], v[200:203], v[120:123]
	v_mfma_f32_16x16x32_bf16 v[108:111], v[32:35], v[208:211], v[108:111]
	v_mfma_f32_16x16x32_bf16 v[104:107], v[40:43], v[208:211], v[104:107]
	v_mfma_f32_16x16x32_bf16 v[92:95], v[32:35], v[216:219], v[92:95]
	v_mfma_f32_16x16x32_bf16 v[88:91], v[40:43], v[216:219], v[88:91]
	v_mfma_f32_16x16x32_bf16 v[140:143], v[36:39], v[196:199], v[140:143]
	v_mfma_f32_16x16x32_bf16 v[136:139], v[44:47], v[196:199], v[136:139]
	v_mfma_f32_16x16x32_bf16 v[124:127], v[36:39], v[204:207], v[124:127]
	v_mfma_f32_16x16x32_bf16 v[120:123], v[44:47], v[204:207], v[120:123]
	v_mfma_f32_16x16x32_bf16 v[108:111], v[36:39], v[212:215], v[108:111]
	v_mfma_f32_16x16x32_bf16 v[104:107], v[44:47], v[212:215], v[104:107]
	v_mfma_f32_16x16x32_bf16 v[92:95], v[36:39], v[220:223], v[92:95]
	v_mfma_f32_16x16x32_bf16 v[88:91], v[44:47], v[220:223], v[88:91]
	s_setprio 0
	s_setprio 1
	v_mfma_f32_16x16x32_bf16 v[132:135], v[144:147], v[192:195], v[132:135]
	v_mfma_f32_16x16x32_bf16 v[128:131], v[152:155], v[192:195], v[128:131]
	v_mfma_f32_16x16x32_bf16 v[116:119], v[144:147], v[200:203], v[116:119]
	v_mfma_f32_16x16x32_bf16 v[112:115], v[152:155], v[200:203], v[112:115]
	v_mfma_f32_16x16x32_bf16 v[100:103], v[144:147], v[208:211], v[100:103]
	v_mfma_f32_16x16x32_bf16 v[96:99], v[152:155], v[208:211], v[96:99]
	v_mfma_f32_16x16x32_bf16 v[84:87], v[144:147], v[216:219], v[84:87]
	v_mfma_f32_16x16x32_bf16 v[80:83], v[152:155], v[216:219], v[80:83]
	v_mfma_f32_16x16x32_bf16 v[132:135], v[148:151], v[196:199], v[132:135]
	v_mfma_f32_16x16x32_bf16 v[128:131], v[156:159], v[196:199], v[128:131]
	v_mfma_f32_16x16x32_bf16 v[116:119], v[148:151], v[204:207], v[116:119]
	v_mfma_f32_16x16x32_bf16 v[112:115], v[156:159], v[204:207], v[112:115]
	v_mfma_f32_16x16x32_bf16 v[100:103], v[148:151], v[212:215], v[100:103]
	v_mfma_f32_16x16x32_bf16 v[96:99], v[156:159], v[212:215], v[96:99]
	v_mfma_f32_16x16x32_bf16 v[84:87], v[148:151], v[220:223], v[84:87]
	v_mfma_f32_16x16x32_bf16 v[80:83], v[156:159], v[220:223], v[80:83]
	s_setprio 0
	s_barrier
	s_add_i32 s34, s80, s60
	v_lshl_add_u64 v[180:181], s[8:9], 0, v[162:163]
	s_mov_b32 m0, s34
	ds_read_b128 v[192:195], v188 offset:16384
	ds_read_b128 v[196:199], v188 offset:17408
	ds_read_b128 v[200:203], v188 offset:18432
	ds_read_b128 v[204:207], v188 offset:19456
	ds_read_b128 v[208:211], v188 offset:20480
	ds_read_b128 v[212:215], v188 offset:21504
	ds_read_b128 v[216:219], v188 offset:22528
	ds_read_b128 v[220:223], v188 offset:23552
	global_load_lds_dwordx4 v[180:181], off
	s_add_i32 m0, s34, 0x2000
	s_add_u32 s34, s8, 0x40000
	v_lshl_add_u64 v[224:225], s[8:9], 0, v[166:167]
	s_addc_u32 s35, s9, 0
	s_add_i32 s49, s81, s60
	global_load_lds_dwordx4 v[224:225], off
	s_waitcnt vmcnt(4)
	s_waitcnt lgkmcnt(0)
	s_barrier
	s_setprio 1
	s_waitcnt lgkmcnt(0)
	v_mfma_f32_16x16x32_bf16 v[76:79], v[32:35], v[192:195], v[76:79]
	v_mfma_f32_16x16x32_bf16 v[72:75], v[40:43], v[192:195], v[72:75]
	v_mfma_f32_16x16x32_bf16 v[60:63], v[32:35], v[200:203], v[60:63]
	v_mfma_f32_16x16x32_bf16 v[56:59], v[40:43], v[200:203], v[56:59]
	v_lshl_add_u64 v[226:227], s[34:35], 0, v[162:163]
	s_mov_b32 m0, s49
	v_lshl_add_u64 v[228:229], s[56:57], 0, v[164:165]
	global_load_lds_dwordx4 v[226:227], off
	v_mfma_f32_16x16x32_bf16 v[28:31], v[32:35], v[208:211], v[28:31]
	v_mfma_f32_16x16x32_bf16 v[24:27], v[40:43], v[208:211], v[24:27]
	v_mfma_f32_16x16x32_bf16 v[12:15], v[32:35], v[216:219], v[12:15]
	v_mfma_f32_16x16x32_bf16 v[8:11], v[40:43], v[216:219], v[8:11]
	v_mfma_f32_16x16x32_bf16 v[76:79], v[36:39], v[196:199], v[76:79]
	v_mfma_f32_16x16x32_bf16 v[72:75], v[44:47], v[196:199], v[72:75]
	v_lshl_add_u64 v[226:227], s[34:35], 0, v[166:167]
	s_add_i32 m0, s49, 0x2000
	s_nop 0
	global_load_lds_dwordx4 v[226:227], off
	v_mfma_f32_16x16x32_bf16 v[60:63], v[36:39], v[204:207], v[60:63]
	v_mfma_f32_16x16x32_bf16 v[56:59], v[44:47], v[204:207], v[56:59]
	v_mfma_f32_16x16x32_bf16 v[28:31], v[36:39], v[212:215], v[28:31]
	v_mfma_f32_16x16x32_bf16 v[24:27], v[44:47], v[212:215], v[24:27]
	v_mfma_f32_16x16x32_bf16 v[12:15], v[36:39], v[220:223], v[12:15]
	v_mfma_f32_16x16x32_bf16 v[8:11], v[44:47], v[220:223], v[8:11]
	s_setprio 0
	s_setprio 1
	v_mfma_f32_16x16x32_bf16 v[20:23], v[144:147], v[208:211], v[20:23]
	v_mfma_f32_16x16x32_bf16 v[16:19], v[152:155], v[208:211], v[16:19]
	v_lshl_add_u64 v[226:227], s[56:57], 0, v[160:161]
	s_mov_b32 m0, s61
	s_nop 0
	global_load_lds_dwordx4 v[226:227], off
	v_mfma_f32_16x16x32_bf16 v[4:7], v[144:147], v[216:219], v[4:7]
	v_mfma_f32_16x16x32_bf16 v[0:3], v[152:155], v[216:219], v[0:3]
	v_mfma_f32_16x16x32_bf16 v[32:35], v[144:147], v[192:195], v[68:71]
	v_mfma_f32_16x16x32_bf16 v[36:39], v[152:155], v[192:195], v[64:67]
	v_mfma_f32_16x16x32_bf16 v[40:43], v[144:147], v[200:203], v[52:55]
	v_mfma_f32_16x16x32_bf16 v[44:47], v[152:155], v[200:203], v[48:51]
	s_mov_b32 m0, s62
	s_nop 0
	global_load_lds_dwordx4 v[228:229], off
	v_mfma_f32_16x16x32_bf16 v[20:23], v[148:151], v[212:215], v[20:23]
	v_mfma_f32_16x16x32_bf16 v[16:19], v[156:159], v[212:215], v[16:19]
	v_mfma_f32_16x16x32_bf16 v[4:7], v[148:151], v[220:223], v[4:7]
	v_mfma_f32_16x16x32_bf16 v[0:3], v[156:159], v[220:223], v[0:3]
	v_mfma_f32_16x16x32_bf16 v[32:35], v[148:151], v[196:199], v[32:35]
	v_mfma_f32_16x16x32_bf16 v[36:39], v[156:159], v[196:199], v[36:39]
	v_mfma_f32_16x16x32_bf16 v[40:43], v[148:151], v[204:207], v[40:43]
	v_mfma_f32_16x16x32_bf16 v[44:47], v[156:159], v[204:207], v[44:47]
	s_setprio 0
	s_barrier
	s_add_i32 s49, 0, 0x18000
	s_add_i32 s51, 0, 0x1c000
	v_add_u32_e32 v68, s49, v183
	v_add_u32_e32 v156, s51, v183
	ds_read_b128 v[48:51], v68
	ds_read_b128 v[52:55], v68 offset:1024
	ds_read_b128 v[64:67], v68 offset:2048
	ds_read_b128 v[68:71], v68 offset:3072
	ds_read_b128 v[144:147], v156
	ds_read_b128 v[148:151], v156 offset:1024
	ds_read_b128 v[152:155], v156 offset:2048
	ds_read_b128 v[156:159], v156 offset:3072
	s_add_u32 s34, s56, 0x40000
	s_addc_u32 s35, s57, 0
	s_mov_b32 m0, s63
	v_lshl_add_u64 v[230:231], s[34:35], 0, v[160:161]
	ds_read_b128 v[192:195], v188 offset:32768
	ds_read_b128 v[196:199], v188 offset:33792
	ds_read_b128 v[200:203], v188 offset:34816
	ds_read_b128 v[204:207], v188 offset:35840
	ds_read_b128 v[208:211], v188 offset:36864
	ds_read_b128 v[212:215], v188 offset:37888
	ds_read_b128 v[216:219], v188 offset:38912
	ds_read_b128 v[220:223], v188 offset:39936
	global_load_lds_dwordx4 v[230:231], off
	v_lshl_add_u64 v[230:231], s[34:35], 0, v[164:165]
	s_mov_b32 m0, s64
	s_nop 0
	global_load_lds_dwordx4 v[230:231], off
	s_waitcnt vmcnt(8)
	s_waitcnt lgkmcnt(0)
	s_barrier
	s_setprio 1
	s_waitcnt lgkmcnt(0)
	v_mfma_f32_16x16x32_bf16 v[140:143], v[48:51], v[192:195], v[140:143]
	v_mfma_f32_16x16x32_bf16 v[136:139], v[64:67], v[192:195], v[136:139]
	v_mfma_f32_16x16x32_bf16 v[124:127], v[48:51], v[200:203], v[124:127]
	v_mfma_f32_16x16x32_bf16 v[120:123], v[64:67], v[200:203], v[120:123]
	v_mfma_f32_16x16x32_bf16 v[108:111], v[48:51], v[208:211], v[108:111]
	v_mfma_f32_16x16x32_bf16 v[104:107], v[64:67], v[208:211], v[104:107]
	v_mfma_f32_16x16x32_bf16 v[92:95], v[48:51], v[216:219], v[92:95]
	v_mfma_f32_16x16x32_bf16 v[88:91], v[64:67], v[216:219], v[88:91]
	v_mfma_f32_16x16x32_bf16 v[140:143], v[52:55], v[196:199], v[140:143]
	v_mfma_f32_16x16x32_bf16 v[136:139], v[68:71], v[196:199], v[136:139]
	v_mfma_f32_16x16x32_bf16 v[124:127], v[52:55], v[204:207], v[124:127]
	v_mfma_f32_16x16x32_bf16 v[120:123], v[68:71], v[204:207], v[120:123]
	v_mfma_f32_16x16x32_bf16 v[108:111], v[52:55], v[212:215], v[108:111]
	v_mfma_f32_16x16x32_bf16 v[104:107], v[68:71], v[212:215], v[104:107]
	v_mfma_f32_16x16x32_bf16 v[92:95], v[52:55], v[220:223], v[92:95]
	v_mfma_f32_16x16x32_bf16 v[88:91], v[68:71], v[220:223], v[88:91]
	s_setprio 0
	s_setprio 1
	v_mfma_f32_16x16x32_bf16 v[132:135], v[144:147], v[192:195], v[132:135]
	v_mfma_f32_16x16x32_bf16 v[128:131], v[152:155], v[192:195], v[128:131]
	v_mfma_f32_16x16x32_bf16 v[116:119], v[144:147], v[200:203], v[116:119]
	v_mfma_f32_16x16x32_bf16 v[112:115], v[152:155], v[200:203], v[112:115]
	v_mfma_f32_16x16x32_bf16 v[100:103], v[144:147], v[208:211], v[100:103]
	v_mfma_f32_16x16x32_bf16 v[96:99], v[152:155], v[208:211], v[96:99]
	v_mfma_f32_16x16x32_bf16 v[84:87], v[144:147], v[216:219], v[84:87]
	v_mfma_f32_16x16x32_bf16 v[80:83], v[152:155], v[216:219], v[80:83]
	v_mfma_f32_16x16x32_bf16 v[132:135], v[148:151], v[196:199], v[132:135]
	v_mfma_f32_16x16x32_bf16 v[128:131], v[156:159], v[196:199], v[128:131]
	v_mfma_f32_16x16x32_bf16 v[116:119], v[148:151], v[204:207], v[116:119]
	v_mfma_f32_16x16x32_bf16 v[112:115], v[156:159], v[204:207], v[112:115]
	v_mfma_f32_16x16x32_bf16 v[100:103], v[148:151], v[212:215], v[100:103]
	v_mfma_f32_16x16x32_bf16 v[96:99], v[156:159], v[212:215], v[96:99]
	v_mfma_f32_16x16x32_bf16 v[84:87], v[148:151], v[220:223], v[84:87]
	v_mfma_f32_16x16x32_bf16 v[80:83], v[156:159], v[220:223], v[80:83]
	s_setprio 0
	s_barrier
	s_add_i32 s34, s49, s60
	v_lshl_add_u64 v[180:181], v[180:181], 0, s[46:47]
	s_mov_b32 m0, s34
	ds_read_b128 v[192:195], v188 offset:49152
	ds_read_b128 v[196:199], v188 offset:50176
	ds_read_b128 v[200:203], v188 offset:51200
	ds_read_b128 v[204:207], v188 offset:52224
	ds_read_b128 v[208:211], v188 offset:53248
	ds_read_b128 v[212:215], v188 offset:54272
	ds_read_b128 v[216:219], v188 offset:55296
	ds_read_b128 v[220:223], v188 offset:56320
	global_load_lds_dwordx4 v[180:181], off
	s_add_i32 m0, s34, 0x2000
	s_add_u32 s8, s8, 0x40080
	v_lshl_add_u64 v[180:181], v[224:225], 0, s[46:47]
	s_addc_u32 s9, s9, 0
	s_add_i32 s34, s51, s60
	global_load_lds_dwordx4 v[180:181], off
	s_waitcnt vmcnt(4)
	s_waitcnt lgkmcnt(0)
	s_barrier
	s_setprio 1
	s_waitcnt lgkmcnt(0)
	v_mfma_f32_16x16x32_bf16 v[76:79], v[48:51], v[192:195], v[76:79]
	v_mfma_f32_16x16x32_bf16 v[72:75], v[64:67], v[192:195], v[72:75]
	v_mfma_f32_16x16x32_bf16 v[60:63], v[48:51], v[200:203], v[60:63]
	v_mfma_f32_16x16x32_bf16 v[56:59], v[64:67], v[200:203], v[56:59]
	v_lshl_add_u64 v[180:181], s[8:9], 0, v[162:163]
	s_mov_b32 m0, s34
	s_nop 0
	global_load_lds_dwordx4 v[180:181], off
	v_mfma_f32_16x16x32_bf16 v[28:31], v[48:51], v[208:211], v[28:31]
	v_mfma_f32_16x16x32_bf16 v[24:27], v[64:67], v[208:211], v[24:27]
	v_mfma_f32_16x16x32_bf16 v[12:15], v[48:51], v[216:219], v[12:15]
	v_mfma_f32_16x16x32_bf16 v[8:11], v[64:67], v[216:219], v[8:11]
	v_mfma_f32_16x16x32_bf16 v[76:79], v[52:55], v[196:199], v[76:79]
	v_mfma_f32_16x16x32_bf16 v[72:75], v[68:71], v[196:199], v[72:75]
	v_lshl_add_u64 v[180:181], s[8:9], 0, v[166:167]
	s_add_i32 m0, s34, 0x2000
	s_nop 0
	global_load_lds_dwordx4 v[180:181], off
	v_mfma_f32_16x16x32_bf16 v[60:63], v[52:55], v[204:207], v[60:63]
	v_mfma_f32_16x16x32_bf16 v[56:59], v[68:71], v[204:207], v[56:59]
	v_mfma_f32_16x16x32_bf16 v[28:31], v[52:55], v[212:215], v[28:31]
	v_mfma_f32_16x16x32_bf16 v[24:27], v[68:71], v[212:215], v[24:27]
	v_mfma_f32_16x16x32_bf16 v[12:15], v[52:55], v[220:223], v[12:15]
	v_mfma_f32_16x16x32_bf16 v[8:11], v[68:71], v[220:223], v[8:11]
	s_setprio 0
	s_setprio 1
	v_mfma_f32_16x16x32_bf16 v[32:35], v[144:147], v[192:195], v[32:35]
	v_mfma_f32_16x16x32_bf16 v[68:71], v[148:151], v[196:199], v[32:35]
	v_lshl_add_u64 v[180:181], v[226:227], 0, s[46:47]
	s_mov_b32 m0, s78
	s_nop 0
	global_load_lds_dwordx4 v[180:181], off
	v_mfma_f32_16x16x32_bf16 v[32:35], v[152:155], v[192:195], v[36:39]
	v_mfma_f32_16x16x32_bf16 v[64:67], v[156:159], v[196:199], v[32:35]
	v_mfma_f32_16x16x32_bf16 v[32:35], v[144:147], v[200:203], v[40:43]
	v_mfma_f32_16x16x32_bf16 v[52:55], v[148:151], v[204:207], v[32:35]
	v_mfma_f32_16x16x32_bf16 v[32:35], v[152:155], v[200:203], v[44:47]
	v_mfma_f32_16x16x32_bf16 v[20:23], v[144:147], v[208:211], v[20:23]
	v_lshl_add_u64 v[180:181], v[228:229], 0, s[46:47]
	s_mov_b32 m0, s79
	s_nop 0
	global_load_lds_dwordx4 v[180:181], off
	v_mfma_f32_16x16x32_bf16 v[16:19], v[152:155], v[208:211], v[16:19]
	v_mfma_f32_16x16x32_bf16 v[4:7], v[144:147], v[216:219], v[4:7]
	v_mfma_f32_16x16x32_bf16 v[0:3], v[152:155], v[216:219], v[0:3]
	v_mfma_f32_16x16x32_bf16 v[48:51], v[156:159], v[204:207], v[32:35]
	v_mfma_f32_16x16x32_bf16 v[20:23], v[148:151], v[212:215], v[20:23]
	v_mfma_f32_16x16x32_bf16 v[16:19], v[156:159], v[212:215], v[16:19]
	v_mfma_f32_16x16x32_bf16 v[4:7], v[148:151], v[220:223], v[4:7]
	v_mfma_f32_16x16x32_bf16 v[0:3], v[156:159], v[220:223], v[0:3]
	s_setprio 0
	s_barrier
	s_add_i32 s33, s33, 2
	s_add_u32 s6, s6, 0x100
	s_addc_u32 s7, s7, 0
	s_add_u32 s25, s25, 0x100
	s_addc_u32 s30, s30, 0
	s_cmp_gt_u32 s33, 13
	s_cbranch_scc0 .LBB5_625
	s_nop 0
	s_nop 0
	s_nop 0
	s_nop 0
	s_nop 0
	s_nop 0
	s_nop 0
	s_nop 0
	s_nop 0
	s_nop 0
	s_nop 0
	s_nop 0
	s_nop 0
	s_nop 0
	s_and_b64 vcc, exec, s[42:43]
	s_cbranch_vccz .LBB5_628
	s_barrier

.Lskw_P8:
	s_waitcnt lgkmcnt(0)
	s_barrier
	s_setprio 1
	s_waitcnt lgkmcnt(0)
	v_mfma_f32_16x16x32_bf16 v[124:127], v[128:131], v[176:179], v[124:127]
	v_mfma_f32_16x16x32_bf16 v[120:123], v[136:139], v[176:179], v[120:123]
	v_mfma_f32_16x16x32_bf16 v[108:111], v[128:131], v[194:197], v[108:111]
	v_mfma_f32_16x16x32_bf16 v[104:107], v[136:139], v[194:197], v[104:107]
	v_mfma_f32_16x16x32_bf16 v[92:95], v[128:131], v[202:205], v[92:95]
	v_mfma_f32_16x16x32_bf16 v[88:91], v[136:139], v[202:205], v[88:91]
	v_mfma_f32_16x16x32_bf16 v[76:79], v[128:131], v[210:213], v[76:79]
	v_mfma_f32_16x16x32_bf16 v[72:75], v[136:139], v[210:213], v[72:75]
	v_mfma_f32_16x16x32_bf16 v[124:127], v[132:135], v[180:183], v[124:127]
	v_mfma_f32_16x16x32_bf16 v[120:123], v[140:143], v[180:183], v[120:123]
	v_mfma_f32_16x16x32_bf16 v[108:111], v[132:135], v[198:201], v[108:111]
	v_mfma_f32_16x16x32_bf16 v[104:107], v[140:143], v[198:201], v[104:107]
	v_mfma_f32_16x16x32_bf16 v[92:95], v[132:135], v[206:209], v[92:95]
	v_mfma_f32_16x16x32_bf16 v[88:91], v[140:143], v[206:209], v[88:91]
	v_mfma_f32_16x16x32_bf16 v[76:79], v[132:135], v[214:217], v[76:79]
	v_mfma_f32_16x16x32_bf16 v[72:75], v[140:143], v[214:217], v[72:75]
	s_setprio 0
	s_setprio 1
	v_mfma_f32_16x16x32_bf16 v[116:119], v[144:147], v[176:179], v[116:119]
	v_mfma_f32_16x16x32_bf16 v[112:115], v[168:171], v[176:179], v[112:115]
	v_mfma_f32_16x16x32_bf16 v[100:103], v[144:147], v[194:197], v[100:103]
	v_mfma_f32_16x16x32_bf16 v[96:99], v[168:171], v[194:197], v[96:99]
	v_mfma_f32_16x16x32_bf16 v[84:87], v[144:147], v[202:205], v[84:87]
	v_mfma_f32_16x16x32_bf16 v[80:83], v[168:171], v[202:205], v[80:83]
	v_mfma_f32_16x16x32_bf16 v[68:71], v[144:147], v[210:213], v[68:71]
	v_mfma_f32_16x16x32_bf16 v[64:67], v[168:171], v[210:213], v[64:67]
	v_mfma_f32_16x16x32_bf16 v[116:119], v[148:151], v[180:183], v[116:119]
	v_mfma_f32_16x16x32_bf16 v[112:115], v[172:175], v[180:183], v[112:115]
	v_mfma_f32_16x16x32_bf16 v[100:103], v[148:151], v[198:201], v[100:103]
	v_mfma_f32_16x16x32_bf16 v[96:99], v[172:175], v[198:201], v[96:99]
	v_mfma_f32_16x16x32_bf16 v[84:87], v[148:151], v[206:209], v[84:87]
	v_mfma_f32_16x16x32_bf16 v[80:83], v[172:175], v[206:209], v[80:83]
	v_mfma_f32_16x16x32_bf16 v[68:71], v[148:151], v[214:217], v[68:71]
	v_mfma_f32_16x16x32_bf16 v[64:67], v[172:175], v[214:217], v[64:67]
	s_setprio 0
	s_barrier
	s_add_i32 s58, s51, s33
	v_lshl_add_u64 v[184:185], s[40:41], 0, v[154:155]
	s_mov_b32 m0, s58
	ds_read_b128 v[176:179], v193 offset:16384
	ds_read_b128 v[180:183], v193 offset:17408
	ds_read_b128 v[194:197], v193 offset:18432
	ds_read_b128 v[198:201], v193 offset:19456
	ds_read_b128 v[202:205], v193 offset:20480
	ds_read_b128 v[206:209], v193 offset:21504
	ds_read_b128 v[210:213], v193 offset:22528
	ds_read_b128 v[214:217], v193 offset:23552
	global_load_lds_dwordx4 v[184:185], off
	s_add_i32 m0, s58, 0x2000
	s_add_u32 s58, s40, 0x40000
	v_lshl_add_u64 v[218:219], s[40:41], 0, v[158:159]
	s_addc_u32 s59, s41, 0
	s_add_i32 s60, s52, s33
	global_load_lds_dwordx4 v[218:219], off
	s_waitcnt vmcnt(4)
	s_waitcnt lgkmcnt(0)
	s_barrier
	s_setprio 1
	s_waitcnt lgkmcnt(0)
	v_mfma_f32_16x16x32_bf16 v[60:63], v[128:131], v[176:179], v[60:63]
	v_mfma_f32_16x16x32_bf16 v[56:59], v[136:139], v[176:179], v[56:59]
	v_mfma_f32_16x16x32_bf16 v[44:47], v[128:131], v[194:197], v[44:47]
	v_mfma_f32_16x16x32_bf16 v[40:43], v[136:139], v[194:197], v[40:43]
	v_lshl_add_u64 v[220:221], s[58:59], 0, v[154:155]
	s_mov_b32 m0, s60
	v_lshl_add_u64 v[222:223], s[42:43], 0, v[156:157]
	global_load_lds_dwordx4 v[220:221], off
	v_mfma_f32_16x16x32_bf16 v[28:31], v[128:131], v[202:205], v[28:31]
	v_mfma_f32_16x16x32_bf16 v[24:27], v[136:139], v[202:205], v[24:27]
	v_mfma_f32_16x16x32_bf16 v[12:15], v[128:131], v[210:213], v[12:15]
	v_mfma_f32_16x16x32_bf16 v[8:11], v[136:139], v[210:213], v[8:11]
	v_mfma_f32_16x16x32_bf16 v[60:63], v[132:135], v[180:183], v[60:63]
	v_mfma_f32_16x16x32_bf16 v[56:59], v[140:143], v[180:183], v[56:59]
	v_lshl_add_u64 v[220:221], s[58:59], 0, v[158:159]
	s_add_i32 m0, s60, 0x2000
	s_nop 0
	global_load_lds_dwordx4 v[220:221], off
	v_mfma_f32_16x16x32_bf16 v[44:47], v[132:135], v[198:201], v[44:47]
	v_mfma_f32_16x16x32_bf16 v[40:43], v[140:143], v[198:201], v[40:43]
	v_mfma_f32_16x16x32_bf16 v[28:31], v[132:135], v[206:209], v[28:31]
	v_mfma_f32_16x16x32_bf16 v[24:27], v[140:143], v[206:209], v[24:27]
	v_mfma_f32_16x16x32_bf16 v[12:15], v[132:135], v[214:217], v[12:15]
	v_mfma_f32_16x16x32_bf16 v[8:11], v[140:143], v[214:217], v[8:11]
	s_setprio 0
	s_setprio 1
	v_mfma_f32_16x16x32_bf16 v[52:55], v[144:147], v[176:179], v[52:55]
	v_mfma_f32_16x16x32_bf16 v[48:51], v[168:171], v[176:179], v[48:51]
	v_lshl_add_u64 v[220:221], s[42:43], 0, v[152:153]
	s_mov_b32 m0, s34
	s_nop 0
	global_load_lds_dwordx4 v[220:221], off
	v_mfma_f32_16x16x32_bf16 v[36:39], v[144:147], v[194:197], v[36:39]
	v_mfma_f32_16x16x32_bf16 v[32:35], v[168:171], v[194:197], v[32:35]
	v_mfma_f32_16x16x32_bf16 v[20:23], v[144:147], v[202:205], v[20:23]
	v_mfma_f32_16x16x32_bf16 v[16:19], v[168:171], v[202:205], v[16:19]
	v_mfma_f32_16x16x32_bf16 v[4:7], v[144:147], v[210:213], v[4:7]
	v_mfma_f32_16x16x32_bf16 v[0:3], v[168:171], v[210:213], v[0:3]
	s_mov_b32 m0, s35
	s_nop 0
	global_load_lds_dwordx4 v[222:223], off
	v_mfma_f32_16x16x32_bf16 v[52:55], v[148:151], v[180:183], v[52:55]
	v_mfma_f32_16x16x32_bf16 v[48:51], v[172:175], v[180:183], v[48:51]
	v_mfma_f32_16x16x32_bf16 v[36:39], v[148:151], v[198:201], v[36:39]
	v_mfma_f32_16x16x32_bf16 v[32:35], v[172:175], v[198:201], v[32:35]
	v_mfma_f32_16x16x32_bf16 v[20:23], v[148:151], v[206:209], v[20:23]
	v_mfma_f32_16x16x32_bf16 v[16:19], v[172:175], v[206:209], v[16:19]
	v_mfma_f32_16x16x32_bf16 v[4:7], v[148:151], v[214:217], v[4:7]
	v_mfma_f32_16x16x32_bf16 v[0:3], v[172:175], v[214:217], v[0:3]
	s_setprio 0
	s_barrier
	s_add_i32 s58, 0, 0x18000
	s_add_i32 s59, 0, 0x1c000
	v_add_u32_e32 v140, s58, v187
	v_add_u32_e32 v172, s59, v187
	ds_read_b128 v[128:131], v140
	ds_read_b128 v[132:135], v140 offset:1024
	ds_read_b128 v[136:139], v140 offset:2048
	ds_read_b128 v[140:143], v140 offset:3072
	ds_read_b128 v[144:147], v172
	ds_read_b128 v[148:151], v172 offset:1024
	ds_read_b128 v[168:171], v172 offset:2048
	ds_read_b128 v[172:175], v172 offset:3072
	s_add_u32 s42, s42, 0x40000
	s_addc_u32 s43, s43, 0
	s_mov_b32 m0, s44
	v_lshl_add_u64 v[224:225], s[42:43], 0, v[152:153]
	ds_read_b128 v[176:179], v193 offset:32768
	ds_read_b128 v[180:183], v193 offset:33792
	ds_read_b128 v[194:197], v193 offset:34816
	ds_read_b128 v[198:201], v193 offset:35840
	ds_read_b128 v[202:205], v193 offset:36864
	ds_read_b128 v[206:209], v193 offset:37888
	ds_read_b128 v[210:213], v193 offset:38912
	ds_read_b128 v[214:217], v193 offset:39936
	global_load_lds_dwordx4 v[224:225], off
	v_lshl_add_u64 v[224:225], s[42:43], 0, v[156:157]
	s_mov_b32 m0, s45
	s_nop 0
	global_load_lds_dwordx4 v[224:225], off
	s_waitcnt vmcnt(8)
	s_waitcnt lgkmcnt(0)
	s_barrier
	s_setprio 1
	s_waitcnt lgkmcnt(0)
	v_mfma_f32_16x16x32_bf16 v[124:127], v[128:131], v[176:179], v[124:127]
	v_mfma_f32_16x16x32_bf16 v[120:123], v[136:139], v[176:179], v[120:123]
	v_mfma_f32_16x16x32_bf16 v[108:111], v[128:131], v[194:197], v[108:111]
	v_mfma_f32_16x16x32_bf16 v[104:107], v[136:139], v[194:197], v[104:107]
	v_mfma_f32_16x16x32_bf16 v[92:95], v[128:131], v[202:205], v[92:95]
	v_mfma_f32_16x16x32_bf16 v[88:91], v[136:139], v[202:205], v[88:91]
	v_mfma_f32_16x16x32_bf16 v[76:79], v[128:131], v[210:213], v[76:79]
	v_mfma_f32_16x16x32_bf16 v[72:75], v[136:139], v[210:213], v[72:75]
	v_mfma_f32_16x16x32_bf16 v[124:127], v[132:135], v[180:183], v[124:127]
	v_mfma_f32_16x16x32_bf16 v[120:123], v[140:143], v[180:183], v[120:123]
	v_mfma_f32_16x16x32_bf16 v[108:111], v[132:135], v[198:201], v[108:111]
	v_mfma_f32_16x16x32_bf16 v[104:107], v[140:143], v[198:201], v[104:107]
	v_mfma_f32_16x16x32_bf16 v[92:95], v[132:135], v[206:209], v[92:95]
	v_mfma_f32_16x16x32_bf16 v[88:91], v[140:143], v[206:209], v[88:91]
	v_mfma_f32_16x16x32_bf16 v[76:79], v[132:135], v[214:217], v[76:79]
	v_mfma_f32_16x16x32_bf16 v[72:75], v[140:143], v[214:217], v[72:75]
	s_setprio 0
	s_setprio 1
	v_mfma_f32_16x16x32_bf16 v[116:119], v[144:147], v[176:179], v[116:119]
	v_mfma_f32_16x16x32_bf16 v[112:115], v[168:171], v[176:179], v[112:115]
	v_mfma_f32_16x16x32_bf16 v[100:103], v[144:147], v[194:197], v[100:103]
	v_mfma_f32_16x16x32_bf16 v[96:99], v[168:171], v[194:197], v[96:99]
	v_mfma_f32_16x16x32_bf16 v[84:87], v[144:147], v[202:205], v[84:87]
	v_mfma_f32_16x16x32_bf16 v[80:83], v[168:171], v[202:205], v[80:83]
	v_mfma_f32_16x16x32_bf16 v[68:71], v[144:147], v[210:213], v[68:71]
	v_mfma_f32_16x16x32_bf16 v[64:67], v[168:171], v[210:213], v[64:67]
	v_mfma_f32_16x16x32_bf16 v[116:119], v[148:151], v[180:183], v[116:119]
	v_mfma_f32_16x16x32_bf16 v[112:115], v[172:175], v[180:183], v[112:115]
	v_mfma_f32_16x16x32_bf16 v[100:103], v[148:151], v[198:201], v[100:103]
	v_mfma_f32_16x16x32_bf16 v[96:99], v[172:175], v[198:201], v[96:99]
	v_mfma_f32_16x16x32_bf16 v[84:87], v[148:151], v[206:209], v[84:87]
	v_mfma_f32_16x16x32_bf16 v[80:83], v[172:175], v[206:209], v[80:83]
	v_mfma_f32_16x16x32_bf16 v[68:71], v[148:151], v[214:217], v[68:71]
	v_mfma_f32_16x16x32_bf16 v[64:67], v[172:175], v[214:217], v[64:67]
	s_setprio 0
	s_barrier
	s_add_i32 s42, s58, s33
	v_lshl_add_u64 v[184:185], v[184:185], 0, s[18:19]
	s_mov_b32 m0, s42
	ds_read_b128 v[176:179], v193 offset:49152
	ds_read_b128 v[180:183], v193 offset:50176
	ds_read_b128 v[194:197], v193 offset:51200
	ds_read_b128 v[198:201], v193 offset:52224
	ds_read_b128 v[202:205], v193 offset:53248
	ds_read_b128 v[206:209], v193 offset:54272
	ds_read_b128 v[210:213], v193 offset:55296
	ds_read_b128 v[214:217], v193 offset:56320
	global_load_lds_dwordx4 v[184:185], off
	s_add_i32 m0, s42, 0x2000
	s_add_u32 s40, s40, 0x40080
	v_lshl_add_u64 v[184:185], v[218:219], 0, s[18:19]
	s_addc_u32 s41, s41, 0
	s_add_i32 s42, s59, s33
	global_load_lds_dwordx4 v[184:185], off
	s_waitcnt vmcnt(4)
	s_waitcnt lgkmcnt(0)
	s_barrier
	s_setprio 1
	s_waitcnt lgkmcnt(0)
	v_mfma_f32_16x16x32_bf16 v[60:63], v[128:131], v[176:179], v[60:63]
	v_mfma_f32_16x16x32_bf16 v[56:59], v[136:139], v[176:179], v[56:59]
	v_mfma_f32_16x16x32_bf16 v[44:47], v[128:131], v[194:197], v[44:47]
	v_mfma_f32_16x16x32_bf16 v[40:43], v[136:139], v[194:197], v[40:43]
	v_lshl_add_u64 v[184:185], s[40:41], 0, v[154:155]
	s_mov_b32 m0, s42
	s_nop 0
	global_load_lds_dwordx4 v[184:185], off
	v_mfma_f32_16x16x32_bf16 v[28:31], v[128:131], v[202:205], v[28:31]
	v_mfma_f32_16x16x32_bf16 v[24:27], v[136:139], v[202:205], v[24:27]
	v_mfma_f32_16x16x32_bf16 v[12:15], v[128:131], v[210:213], v[12:15]
	v_mfma_f32_16x16x32_bf16 v[8:11], v[136:139], v[210:213], v[8:11]
	v_mfma_f32_16x16x32_bf16 v[60:63], v[132:135], v[180:183], v[60:63]
	v_mfma_f32_16x16x32_bf16 v[56:59], v[140:143], v[180:183], v[56:59]
	v_lshl_add_u64 v[184:185], s[40:41], 0, v[158:159]
	s_add_i32 m0, s42, 0x2000
	s_nop 0
	global_load_lds_dwordx4 v[184:185], off
	v_mfma_f32_16x16x32_bf16 v[44:47], v[132:135], v[198:201], v[44:47]
	v_mfma_f32_16x16x32_bf16 v[40:43], v[140:143], v[198:201], v[40:43]
	v_mfma_f32_16x16x32_bf16 v[28:31], v[132:135], v[206:209], v[28:31]
	v_mfma_f32_16x16x32_bf16 v[24:27], v[140:143], v[206:209], v[24:27]
	v_mfma_f32_16x16x32_bf16 v[12:15], v[132:135], v[214:217], v[12:15]
	v_mfma_f32_16x16x32_bf16 v[8:11], v[140:143], v[214:217], v[8:11]
	s_setprio 0
	s_setprio 1
	v_mfma_f32_16x16x32_bf16 v[52:55], v[144:147], v[176:179], v[52:55]
	v_mfma_f32_16x16x32_bf16 v[48:51], v[168:171], v[176:179], v[48:51]
	v_lshl_add_u64 v[184:185], v[220:221], 0, s[18:19]
	s_mov_b32 m0, s49
	s_nop 0
	global_load_lds_dwordx4 v[184:185], off
	v_mfma_f32_16x16x32_bf16 v[36:39], v[144:147], v[194:197], v[36:39]
	v_mfma_f32_16x16x32_bf16 v[32:35], v[168:171], v[194:197], v[32:35]
	v_mfma_f32_16x16x32_bf16 v[20:23], v[144:147], v[202:205], v[20:23]
	v_mfma_f32_16x16x32_bf16 v[16:19], v[168:171], v[202:205], v[16:19]
	v_mfma_f32_16x16x32_bf16 v[4:7], v[144:147], v[210:213], v[4:7]
	v_mfma_f32_16x16x32_bf16 v[0:3], v[168:171], v[210:213], v[0:3]
	v_lshl_add_u64 v[184:185], v[222:223], 0, s[18:19]
	s_mov_b32 m0, s50
	s_nop 0
	global_load_lds_dwordx4 v[184:185], off
	v_mfma_f32_16x16x32_bf16 v[52:55], v[148:151], v[180:183], v[52:55]
	v_mfma_f32_16x16x32_bf16 v[48:51], v[172:175], v[180:183], v[48:51]
	v_mfma_f32_16x16x32_bf16 v[36:39], v[148:151], v[198:201], v[36:39]
	v_mfma_f32_16x16x32_bf16 v[32:35], v[172:175], v[198:201], v[32:35]
	v_mfma_f32_16x16x32_bf16 v[20:23], v[148:151], v[206:209], v[20:23]
	v_mfma_f32_16x16x32_bf16 v[16:19], v[172:175], v[206:209], v[16:19]
	v_mfma_f32_16x16x32_bf16 v[4:7], v[148:151], v[214:217], v[4:7]
	v_mfma_f32_16x16x32_bf16 v[0:3], v[172:175], v[214:217], v[0:3]
	s_setprio 0
	s_barrier
	s_add_i32 s57, s57, 2
	s_add_u32 s38, s38, 0x100
	s_addc_u32 s39, s39, 0
	s_add_u32 s55, s55, 0x100
	s_addc_u32 s56, s56, 0
	s_cmp_gt_u32 s57, 13
	s_cbranch_scc0 .LBB5_969
	s_nop 0
	s_nop 0
	s_nop 0
	s_nop 0
	s_nop 0
	s_nop 0
	s_nop 0
	s_nop 0
	s_nop 0
	s_nop 0
	s_nop 0
	s_nop 0
	s_nop 0
	s_nop 0
	s_and_b64 vcc, exec, s[16:17]
	s_cbranch_vccz .LBB5_972
	s_barrier
